# lw: leading ping-pong half defers its DMA-arrival vmcnt waits to after the 32 MFMAs (before its closing barrier) in 5 GEMM K loops; trailing half unchanged
# baseline (speedup 1.0000x reference)
.LBB0_640:
	s_and_b64 vcc, exec, s[4:5]
	s_waitcnt lgkmcnt(0)
	s_cbranch_vccnz .Lzx642
	s_add_u32 s56, s56, 0x80
	s_addc_u32 s57, s57, 0
	s_add_u32 s62, s58, 0x100
	s_addc_u32 s63, s59, 0
	s_mov_b32 s58, 0
	s_and_b64 vcc, exec, s[94:95]
	ds_read_b128 v[146:149], v153
	ds_read_b128 v[156:159], v153 offset:1024
	ds_read_b128 v[160:163], v153 offset:2048
	ds_read_b128 v[164:167], v153 offset:3072
	ds_read_b128 v[168:171], v154
	ds_read_b128 v[172:175], v154 offset:1024
	ds_read_b128 v[176:179], v154 offset:2048
	ds_read_b128 v[180:183], v154 offset:3072
	s_add_i32 s64, s58, 2
	s_add_u32 s65, s56, 0x80
	s_addc_u32 s59, s57, 0
	s_cmp_eq_u32 s49, s58
	s_cselect_b32 s58, s8, s65
	s_cselect_b32 s59, s9, s59
	s_cselect_b32 s67, s43, s63
	s_cselect_b32 s66, s42, s62
	v_lshl_add_u64 v[224:225], s[56:57], 0, v[138:139]
	s_add_i32 m0, s3, 0xc000
	ds_read_b128 v[186:189], v155
	ds_read_b128 v[190:193], v155 offset:1024
	ds_read_b128 v[194:197], v155 offset:2048
	ds_read_b128 v[198:201], v155 offset:3072
	ds_read_b128 v[202:205], v155 offset:4096
	ds_read_b128 v[206:209], v155 offset:5120
	ds_read_b128 v[210:213], v155 offset:6144
	ds_read_b128 v[214:217], v155 offset:7168
	global_load_lds_dwordx4 v[224:225], off
	v_lshl_add_u64 v[224:225], s[56:57], 0, v[140:141]
	s_add_i32 m0, s3, 0xe000
	s_nop 0
	global_load_lds_dwordx4 v[224:225], off
	s_cbranch_vccnz .Llw642pw0
	s_waitcnt vmcnt(8)
.Llw642pw0:
	s_waitcnt lgkmcnt(0)
	s_barrier
	s_setprio 1
	s_waitcnt lgkmcnt(0)
	v_mfma_f32_16x16x32_bf16 v[124:127], v[146:149], v[186:189], 0
	v_mfma_f32_16x16x32_bf16 v[120:123], v[160:163], v[186:189], 0
	v_mfma_f32_16x16x32_bf16 v[108:111], v[146:149], v[194:197], 0
	v_mfma_f32_16x16x32_bf16 v[104:107], v[160:163], v[194:197], 0
	v_mfma_f32_16x16x32_bf16 v[92:95], v[146:149], v[202:205], 0
	v_mfma_f32_16x16x32_bf16 v[88:91], v[160:163], v[202:205], 0
	v_mfma_f32_16x16x32_bf16 v[76:79], v[146:149], v[210:213], 0
	v_mfma_f32_16x16x32_bf16 v[72:75], v[160:163], v[210:213], 0
	v_mfma_f32_16x16x32_bf16 v[124:127], v[156:159], v[190:193], v[124:127]
	v_mfma_f32_16x16x32_bf16 v[120:123], v[164:167], v[190:193], v[120:123]
	v_mfma_f32_16x16x32_bf16 v[108:111], v[156:159], v[198:201], v[108:111]
	v_mfma_f32_16x16x32_bf16 v[104:107], v[164:167], v[198:201], v[104:107]
	v_mfma_f32_16x16x32_bf16 v[92:95], v[156:159], v[206:209], v[92:95]
	v_mfma_f32_16x16x32_bf16 v[88:91], v[164:167], v[206:209], v[88:91]
	v_mfma_f32_16x16x32_bf16 v[76:79], v[156:159], v[214:217], v[76:79]
	v_mfma_f32_16x16x32_bf16 v[72:75], v[164:167], v[214:217], v[72:75]
	s_setprio 0
	s_setprio 1
	v_mfma_f32_16x16x32_bf16 v[116:119], v[168:171], v[186:189], 0
	v_mfma_f32_16x16x32_bf16 v[112:115], v[176:179], v[186:189], 0
	v_mfma_f32_16x16x32_bf16 v[100:103], v[168:171], v[194:197], 0
	v_mfma_f32_16x16x32_bf16 v[96:99], v[176:179], v[194:197], 0
	v_mfma_f32_16x16x32_bf16 v[84:87], v[168:171], v[202:205], 0
	v_mfma_f32_16x16x32_bf16 v[80:83], v[176:179], v[202:205], 0
	v_mfma_f32_16x16x32_bf16 v[68:71], v[168:171], v[210:213], 0
	v_mfma_f32_16x16x32_bf16 v[64:67], v[176:179], v[210:213], 0
	v_mfma_f32_16x16x32_bf16 v[116:119], v[172:175], v[190:193], v[116:119]
	v_mfma_f32_16x16x32_bf16 v[112:115], v[180:183], v[190:193], v[112:115]
	v_mfma_f32_16x16x32_bf16 v[100:103], v[172:175], v[198:201], v[100:103]
	v_mfma_f32_16x16x32_bf16 v[96:99], v[180:183], v[198:201], v[96:99]
	v_mfma_f32_16x16x32_bf16 v[84:87], v[172:175], v[206:209], v[84:87]
	v_mfma_f32_16x16x32_bf16 v[80:83], v[180:183], v[206:209], v[80:83]
	v_mfma_f32_16x16x32_bf16 v[68:71], v[172:175], v[214:217], v[68:71]
	v_mfma_f32_16x16x32_bf16 v[64:67], v[180:183], v[214:217], v[64:67]
	s_setprio 0
	s_waitcnt vmcnt(8)
	s_barrier
	s_add_i32 s65, s50, s31
	v_lshl_add_u64 v[224:225], s[66:67], 0, v[130:131]
	s_mov_b32 m0, s65
	ds_read_b128 v[186:189], v155 offset:16384
	ds_read_b128 v[190:193], v155 offset:17408
	ds_read_b128 v[194:197], v155 offset:18432
	ds_read_b128 v[198:201], v155 offset:19456
	ds_read_b128 v[202:205], v155 offset:20480
	ds_read_b128 v[206:209], v155 offset:21504
	ds_read_b128 v[210:213], v155 offset:22528
	ds_read_b128 v[214:217], v155 offset:23552
	global_load_lds_dwordx4 v[224:225], off
	s_add_i32 m0, s65, 0x2000
	v_lshl_add_u64 v[226:227], s[66:67], 0, v[134:135]
	s_add_u32 s66, s66, s18
	s_addc_u32 s67, s67, s19
	s_add_i32 s65, s51, s31
	global_load_lds_dwordx4 v[226:227], off
	v_lshl_add_u64 v[228:229], s[66:67], 0, v[130:131]
	s_mov_b32 m0, s65
	v_lshl_add_u64 v[230:231], s[66:67], 0, v[134:135]
	global_load_lds_dwordx4 v[228:229], off
	s_add_i32 m0, s65, 0x2000
	v_lshl_add_u64 v[232:233], s[58:59], 0, v[128:129]
	global_load_lds_dwordx4 v[230:231], off
	v_lshl_add_u64 v[234:235], s[58:59], 0, v[132:133]
	s_cbranch_vccnz .Llw642pw1
	s_waitcnt vmcnt(6)
.Llw642pw1:
	s_waitcnt lgkmcnt(0)
	s_barrier
	s_setprio 1
	s_waitcnt lgkmcnt(0)
	v_mfma_f32_16x16x32_bf16 v[60:63], v[146:149], v[186:189], 0
	v_mfma_f32_16x16x32_bf16 v[56:59], v[160:163], v[186:189], 0
	v_mfma_f32_16x16x32_bf16 v[44:47], v[146:149], v[194:197], 0
	v_mfma_f32_16x16x32_bf16 v[40:43], v[160:163], v[194:197], 0
	v_mfma_f32_16x16x32_bf16 v[28:31], v[146:149], v[202:205], 0
	v_mfma_f32_16x16x32_bf16 v[24:27], v[160:163], v[202:205], 0
	v_mfma_f32_16x16x32_bf16 v[12:15], v[146:149], v[210:213], 0
	v_mfma_f32_16x16x32_bf16 v[8:11], v[160:163], v[210:213], 0
	v_mfma_f32_16x16x32_bf16 v[60:63], v[156:159], v[190:193], v[60:63]
	v_mfma_f32_16x16x32_bf16 v[56:59], v[164:167], v[190:193], v[56:59]
	v_mfma_f32_16x16x32_bf16 v[44:47], v[156:159], v[198:201], v[44:47]
	v_mfma_f32_16x16x32_bf16 v[40:43], v[164:167], v[198:201], v[40:43]
	v_mfma_f32_16x16x32_bf16 v[28:31], v[156:159], v[206:209], v[28:31]
	v_mfma_f32_16x16x32_bf16 v[24:27], v[164:167], v[206:209], v[24:27]
	v_mfma_f32_16x16x32_bf16 v[12:15], v[156:159], v[214:217], v[12:15]
	v_mfma_f32_16x16x32_bf16 v[8:11], v[164:167], v[214:217], v[8:11]
	s_setprio 0
	s_setprio 1
	v_mfma_f32_16x16x32_bf16 v[52:55], v[168:171], v[186:189], 0
	v_mfma_f32_16x16x32_bf16 v[48:51], v[176:179], v[186:189], 0
	v_mfma_f32_16x16x32_bf16 v[36:39], v[168:171], v[194:197], 0
	v_mfma_f32_16x16x32_bf16 v[32:35], v[176:179], v[194:197], 0
	v_mfma_f32_16x16x32_bf16 v[20:23], v[168:171], v[202:205], 0
	v_mfma_f32_16x16x32_bf16 v[16:19], v[176:179], v[202:205], 0
	v_mfma_f32_16x16x32_bf16 v[4:7], v[168:171], v[210:213], 0
	v_mfma_f32_16x16x32_bf16 v[0:3], v[176:179], v[210:213], 0
	v_mfma_f32_16x16x32_bf16 v[52:55], v[172:175], v[190:193], v[52:55]
	v_mfma_f32_16x16x32_bf16 v[48:51], v[180:183], v[190:193], v[48:51]
	v_mfma_f32_16x16x32_bf16 v[36:39], v[172:175], v[198:201], v[36:39]
	v_mfma_f32_16x16x32_bf16 v[32:35], v[180:183], v[198:201], v[32:35]
	v_mfma_f32_16x16x32_bf16 v[20:23], v[172:175], v[206:209], v[20:23]
	v_mfma_f32_16x16x32_bf16 v[16:19], v[180:183], v[206:209], v[16:19]
	v_mfma_f32_16x16x32_bf16 v[4:7], v[172:175], v[214:217], v[4:7]
	v_mfma_f32_16x16x32_bf16 v[0:3], v[180:183], v[214:217], v[0:3]
	s_setprio 0
	s_waitcnt vmcnt(6)
	s_barrier
	s_add_i32 s65, 0, 0x18000
	v_add_u32_e32 v136, s65, v151
	s_add_i32 s66, 0, 0x1c000
	ds_read_b128 v[146:149], v136
	ds_read_b128 v[156:159], v136 offset:1024
	ds_read_b128 v[160:163], v136 offset:2048
	ds_read_b128 v[164:167], v136 offset:3072
	v_add_u32_e32 v136, s66, v151
	ds_read_b128 v[168:171], v136
	ds_read_b128 v[172:175], v136 offset:1024
	ds_read_b128 v[176:179], v136 offset:2048
	ds_read_b128 v[180:183], v136 offset:3072
	s_add_u32 s58, s58, s18
	s_addc_u32 s59, s59, s19
	s_mov_b32 m0, s3
	s_nop 0
	global_load_lds_dwordx4 v[232:233], off
	s_mov_b32 m0, s28
	s_nop 0
	global_load_lds_dwordx4 v[234:235], off
	s_mov_b32 m0, s33
	v_lshl_add_u64 v[236:237], s[58:59], 0, v[128:129]
	ds_read_b128 v[186:189], v155 offset:32768
	ds_read_b128 v[190:193], v155 offset:33792
	ds_read_b128 v[194:197], v155 offset:34816
	ds_read_b128 v[198:201], v155 offset:35840
	ds_read_b128 v[202:205], v155 offset:36864
	ds_read_b128 v[206:209], v155 offset:37888
	ds_read_b128 v[210:213], v155 offset:38912
	ds_read_b128 v[214:217], v155 offset:39936
	global_load_lds_dwordx4 v[236:237], off
	v_lshl_add_u64 v[236:237], s[58:59], 0, v[132:133]
	s_mov_b32 m0, s44
	s_nop 0
	global_load_lds_dwordx4 v[236:237], off
	s_cbranch_vccnz .Llw642pw2
	s_waitcnt vmcnt(8)
.Llw642pw2:
	s_waitcnt lgkmcnt(0)
	s_barrier
	s_setprio 1
	s_waitcnt lgkmcnt(0)
	v_mfma_f32_16x16x32_bf16 v[124:127], v[146:149], v[186:189], v[124:127]
	v_mfma_f32_16x16x32_bf16 v[120:123], v[160:163], v[186:189], v[120:123]
	v_mfma_f32_16x16x32_bf16 v[108:111], v[146:149], v[194:197], v[108:111]
	v_mfma_f32_16x16x32_bf16 v[104:107], v[160:163], v[194:197], v[104:107]
	v_mfma_f32_16x16x32_bf16 v[92:95], v[146:149], v[202:205], v[92:95]
	v_mfma_f32_16x16x32_bf16 v[88:91], v[160:163], v[202:205], v[88:91]
	v_mfma_f32_16x16x32_bf16 v[76:79], v[146:149], v[210:213], v[76:79]
	v_mfma_f32_16x16x32_bf16 v[72:75], v[160:163], v[210:213], v[72:75]
	v_mfma_f32_16x16x32_bf16 v[124:127], v[156:159], v[190:193], v[124:127]
	v_mfma_f32_16x16x32_bf16 v[120:123], v[164:167], v[190:193], v[120:123]
	v_mfma_f32_16x16x32_bf16 v[108:111], v[156:159], v[198:201], v[108:111]
	v_mfma_f32_16x16x32_bf16 v[104:107], v[164:167], v[198:201], v[104:107]
	v_mfma_f32_16x16x32_bf16 v[92:95], v[156:159], v[206:209], v[92:95]
	v_mfma_f32_16x16x32_bf16 v[88:91], v[164:167], v[206:209], v[88:91]
	v_mfma_f32_16x16x32_bf16 v[76:79], v[156:159], v[214:217], v[76:79]
	v_mfma_f32_16x16x32_bf16 v[72:75], v[164:167], v[214:217], v[72:75]
	s_setprio 0
	s_setprio 1
	v_mfma_f32_16x16x32_bf16 v[116:119], v[168:171], v[186:189], v[116:119]
	v_mfma_f32_16x16x32_bf16 v[112:115], v[176:179], v[186:189], v[112:115]
	v_mfma_f32_16x16x32_bf16 v[100:103], v[168:171], v[194:197], v[100:103]
	v_mfma_f32_16x16x32_bf16 v[96:99], v[176:179], v[194:197], v[96:99]
	v_mfma_f32_16x16x32_bf16 v[84:87], v[168:171], v[202:205], v[84:87]
	v_mfma_f32_16x16x32_bf16 v[80:83], v[176:179], v[202:205], v[80:83]
	v_mfma_f32_16x16x32_bf16 v[68:71], v[168:171], v[210:213], v[68:71]
	v_mfma_f32_16x16x32_bf16 v[64:67], v[176:179], v[210:213], v[64:67]
	v_mfma_f32_16x16x32_bf16 v[116:119], v[172:175], v[190:193], v[116:119]
	v_mfma_f32_16x16x32_bf16 v[112:115], v[180:183], v[190:193], v[112:115]
	v_mfma_f32_16x16x32_bf16 v[100:103], v[172:175], v[198:201], v[100:103]
	v_mfma_f32_16x16x32_bf16 v[96:99], v[180:183], v[198:201], v[96:99]
	v_mfma_f32_16x16x32_bf16 v[84:87], v[172:175], v[206:209], v[84:87]
	v_mfma_f32_16x16x32_bf16 v[80:83], v[180:183], v[206:209], v[80:83]
	v_mfma_f32_16x16x32_bf16 v[68:71], v[172:175], v[214:217], v[68:71]
	v_mfma_f32_16x16x32_bf16 v[64:67], v[180:183], v[214:217], v[64:67]
	s_setprio 0
	s_waitcnt vmcnt(8)
	s_barrier
	s_add_i32 s58, s65, s31
	v_lshl_add_u64 v[224:225], v[224:225], 0, s[40:41]
	s_mov_b32 m0, s58
	ds_read_b128 v[186:189], v155 offset:49152
	ds_read_b128 v[190:193], v155 offset:50176
	ds_read_b128 v[194:197], v155 offset:51200
	ds_read_b128 v[198:201], v155 offset:52224
	ds_read_b128 v[202:205], v155 offset:53248
	ds_read_b128 v[206:209], v155 offset:54272
	ds_read_b128 v[210:213], v155 offset:55296
	ds_read_b128 v[214:217], v155 offset:56320
	global_load_lds_dwordx4 v[224:225], off
	v_lshl_add_u64 v[224:225], v[226:227], 0, s[40:41]
	s_add_i32 m0, s58, 0x2000
	s_add_i32 s58, s66, s31
	global_load_lds_dwordx4 v[224:225], off
	v_lshl_add_u64 v[224:225], v[228:229], 0, s[40:41]
	s_mov_b32 m0, s58
	s_nop 0
	global_load_lds_dwordx4 v[224:225], off
	v_lshl_add_u64 v[224:225], v[230:231], 0, s[40:41]
	s_add_i32 m0, s58, 0x2000
	s_nop 0
	global_load_lds_dwordx4 v[224:225], off
	s_cbranch_vccnz .Llw642pw3
	s_waitcnt vmcnt(6)
.Llw642pw3:
	s_waitcnt lgkmcnt(0)
	s_barrier
	s_setprio 1
	s_waitcnt lgkmcnt(0)
	v_mfma_f32_16x16x32_bf16 v[60:63], v[146:149], v[186:189], v[60:63]
	v_mfma_f32_16x16x32_bf16 v[56:59], v[160:163], v[186:189], v[56:59]
	v_mfma_f32_16x16x32_bf16 v[44:47], v[146:149], v[194:197], v[44:47]
	v_mfma_f32_16x16x32_bf16 v[40:43], v[160:163], v[194:197], v[40:43]
	v_mfma_f32_16x16x32_bf16 v[28:31], v[146:149], v[202:205], v[28:31]
	v_mfma_f32_16x16x32_bf16 v[24:27], v[160:163], v[202:205], v[24:27]
	v_mfma_f32_16x16x32_bf16 v[12:15], v[146:149], v[210:213], v[12:15]
	v_mfma_f32_16x16x32_bf16 v[8:11], v[160:163], v[210:213], v[8:11]
	v_mfma_f32_16x16x32_bf16 v[60:63], v[156:159], v[190:193], v[60:63]
	v_mfma_f32_16x16x32_bf16 v[56:59], v[164:167], v[190:193], v[56:59]
	v_mfma_f32_16x16x32_bf16 v[44:47], v[156:159], v[198:201], v[44:47]
	v_mfma_f32_16x16x32_bf16 v[40:43], v[164:167], v[198:201], v[40:43]
	v_mfma_f32_16x16x32_bf16 v[28:31], v[156:159], v[206:209], v[28:31]
	v_mfma_f32_16x16x32_bf16 v[24:27], v[164:167], v[206:209], v[24:27]
	v_mfma_f32_16x16x32_bf16 v[12:15], v[156:159], v[214:217], v[12:15]
	v_mfma_f32_16x16x32_bf16 v[8:11], v[164:167], v[214:217], v[8:11]
	s_setprio 0
	s_setprio 1
	v_mfma_f32_16x16x32_bf16 v[52:55], v[168:171], v[186:189], v[52:55]
	v_mfma_f32_16x16x32_bf16 v[48:51], v[176:179], v[186:189], v[48:51]
	v_mfma_f32_16x16x32_bf16 v[36:39], v[168:171], v[194:197], v[36:39]
	v_mfma_f32_16x16x32_bf16 v[32:35], v[176:179], v[194:197], v[32:35]
	v_mfma_f32_16x16x32_bf16 v[20:23], v[168:171], v[202:205], v[20:23]
	v_mfma_f32_16x16x32_bf16 v[16:19], v[176:179], v[202:205], v[16:19]
	v_mfma_f32_16x16x32_bf16 v[4:7], v[168:171], v[210:213], v[4:7]
	v_mfma_f32_16x16x32_bf16 v[0:3], v[176:179], v[210:213], v[0:3]
	v_mfma_f32_16x16x32_bf16 v[52:55], v[172:175], v[190:193], v[52:55]
	v_mfma_f32_16x16x32_bf16 v[48:51], v[180:183], v[190:193], v[48:51]
	v_mfma_f32_16x16x32_bf16 v[36:39], v[172:175], v[198:201], v[36:39]
	v_mfma_f32_16x16x32_bf16 v[32:35], v[180:183], v[198:201], v[32:35]
	v_mfma_f32_16x16x32_bf16 v[20:23], v[172:175], v[206:209], v[20:23]
	v_mfma_f32_16x16x32_bf16 v[16:19], v[180:183], v[206:209], v[16:19]
	v_mfma_f32_16x16x32_bf16 v[4:7], v[172:175], v[214:217], v[4:7]
	v_mfma_f32_16x16x32_bf16 v[0:3], v[180:183], v[214:217], v[0:3]
	s_setprio 0
	s_waitcnt vmcnt(6)
	s_barrier
	s_add_u32 s56, s56, 0x100
	s_addc_u32 s57, s57, 0
	s_add_u32 s62, s62, 0x100
	s_addc_u32 s63, s63, 0
	s_cmp_ge_i32 s64, s45
	s_mov_b32 s58, s64
	s_cbranch_scc1 .LBB0_643
.LBB0_642:
	ds_read_b128 v[146:149], v153
	ds_read_b128 v[156:159], v153 offset:1024
	ds_read_b128 v[160:163], v153 offset:2048
	ds_read_b128 v[164:167], v153 offset:3072
	ds_read_b128 v[168:171], v154
	ds_read_b128 v[172:175], v154 offset:1024
	ds_read_b128 v[176:179], v154 offset:2048
	ds_read_b128 v[180:183], v154 offset:3072
	s_add_i32 s64, s58, 2
	s_add_u32 s65, s56, 0x80
	s_addc_u32 s59, s57, 0
	s_cmp_eq_u32 s49, s58
	s_cselect_b32 s58, s8, s65
	s_cselect_b32 s59, s9, s59
	s_cselect_b32 s67, s43, s63
	s_cselect_b32 s66, s42, s62
	v_lshl_add_u64 v[224:225], v[232:233], 0, s[40:41]
	s_mov_b32 m0, s47
	s_nop 0
	global_load_lds_dwordx4 v[224:225], off
	v_lshl_add_u64 v[224:225], v[234:235], 0, s[40:41]
	s_mov_b32 m0, s48
	s_nop 0
	global_load_lds_dwordx4 v[224:225], off
	v_lshl_add_u64 v[224:225], s[56:57], 0, v[138:139]
	s_add_i32 m0, s3, 0xc000
	ds_read_b128 v[186:189], v155
	ds_read_b128 v[190:193], v155 offset:1024
	ds_read_b128 v[194:197], v155 offset:2048
	ds_read_b128 v[198:201], v155 offset:3072
	ds_read_b128 v[202:205], v155 offset:4096
	ds_read_b128 v[206:209], v155 offset:5120
	ds_read_b128 v[210:213], v155 offset:6144
	ds_read_b128 v[214:217], v155 offset:7168
	global_load_lds_dwordx4 v[224:225], off
	v_lshl_add_u64 v[224:225], s[56:57], 0, v[140:141]
	s_add_i32 m0, s3, 0xe000
	s_nop 0
	global_load_lds_dwordx4 v[224:225], off
	s_cbranch_vccnz .Llw642bw0
	s_waitcnt vmcnt(8)
.Llw642bw0:
	s_waitcnt lgkmcnt(0)
	s_barrier
	s_setprio 1
	s_waitcnt lgkmcnt(0)
	v_mfma_f32_16x16x32_bf16 v[124:127], v[146:149], v[186:189], v[124:127]
	v_mfma_f32_16x16x32_bf16 v[120:123], v[160:163], v[186:189], v[120:123]
	v_mfma_f32_16x16x32_bf16 v[108:111], v[146:149], v[194:197], v[108:111]
	v_mfma_f32_16x16x32_bf16 v[104:107], v[160:163], v[194:197], v[104:107]
	v_mfma_f32_16x16x32_bf16 v[92:95], v[146:149], v[202:205], v[92:95]
	v_mfma_f32_16x16x32_bf16 v[88:91], v[160:163], v[202:205], v[88:91]
	v_mfma_f32_16x16x32_bf16 v[76:79], v[146:149], v[210:213], v[76:79]
	v_mfma_f32_16x16x32_bf16 v[72:75], v[160:163], v[210:213], v[72:75]
	v_mfma_f32_16x16x32_bf16 v[124:127], v[156:159], v[190:193], v[124:127]
	v_mfma_f32_16x16x32_bf16 v[120:123], v[164:167], v[190:193], v[120:123]
	v_mfma_f32_16x16x32_bf16 v[108:111], v[156:159], v[198:201], v[108:111]
	v_mfma_f32_16x16x32_bf16 v[104:107], v[164:167], v[198:201], v[104:107]
	v_mfma_f32_16x16x32_bf16 v[92:95], v[156:159], v[206:209], v[92:95]
	v_mfma_f32_16x16x32_bf16 v[88:91], v[164:167], v[206:209], v[88:91]
	v_mfma_f32_16x16x32_bf16 v[76:79], v[156:159], v[214:217], v[76:79]
	v_mfma_f32_16x16x32_bf16 v[72:75], v[164:167], v[214:217], v[72:75]
	s_setprio 0
	s_setprio 1
	v_mfma_f32_16x16x32_bf16 v[116:119], v[168:171], v[186:189], v[116:119]
	v_mfma_f32_16x16x32_bf16 v[112:115], v[176:179], v[186:189], v[112:115]
	v_mfma_f32_16x16x32_bf16 v[100:103], v[168:171], v[194:197], v[100:103]
	v_mfma_f32_16x16x32_bf16 v[96:99], v[176:179], v[194:197], v[96:99]
	v_mfma_f32_16x16x32_bf16 v[84:87], v[168:171], v[202:205], v[84:87]
	v_mfma_f32_16x16x32_bf16 v[80:83], v[176:179], v[202:205], v[80:83]
	v_mfma_f32_16x16x32_bf16 v[68:71], v[168:171], v[210:213], v[68:71]
	v_mfma_f32_16x16x32_bf16 v[64:67], v[176:179], v[210:213], v[64:67]
	v_mfma_f32_16x16x32_bf16 v[116:119], v[172:175], v[190:193], v[116:119]
	v_mfma_f32_16x16x32_bf16 v[112:115], v[180:183], v[190:193], v[112:115]
	v_mfma_f32_16x16x32_bf16 v[100:103], v[172:175], v[198:201], v[100:103]
	v_mfma_f32_16x16x32_bf16 v[96:99], v[180:183], v[198:201], v[96:99]
	v_mfma_f32_16x16x32_bf16 v[84:87], v[172:175], v[206:209], v[84:87]
	v_mfma_f32_16x16x32_bf16 v[80:83], v[180:183], v[206:209], v[80:83]
	v_mfma_f32_16x16x32_bf16 v[68:71], v[172:175], v[214:217], v[68:71]
	v_mfma_f32_16x16x32_bf16 v[64:67], v[180:183], v[214:217], v[64:67]
	s_setprio 0
	s_waitcnt vmcnt(8)
	s_barrier
	s_add_i32 s65, s50, s31
	v_lshl_add_u64 v[224:225], s[66:67], 0, v[130:131]
	s_mov_b32 m0, s65
	ds_read_b128 v[186:189], v155 offset:16384
	ds_read_b128 v[190:193], v155 offset:17408
	ds_read_b128 v[194:197], v155 offset:18432
	ds_read_b128 v[198:201], v155 offset:19456
	ds_read_b128 v[202:205], v155 offset:20480
	ds_read_b128 v[206:209], v155 offset:21504
	ds_read_b128 v[210:213], v155 offset:22528
	ds_read_b128 v[214:217], v155 offset:23552
	global_load_lds_dwordx4 v[224:225], off
	s_add_i32 m0, s65, 0x2000
	v_lshl_add_u64 v[226:227], s[66:67], 0, v[134:135]
	s_add_u32 s66, s66, s18
	s_addc_u32 s67, s67, s19
	s_add_i32 s65, s51, s31
	global_load_lds_dwordx4 v[226:227], off
	v_lshl_add_u64 v[228:229], s[66:67], 0, v[130:131]
	s_mov_b32 m0, s65
	v_lshl_add_u64 v[230:231], s[66:67], 0, v[134:135]
	global_load_lds_dwordx4 v[228:229], off
	s_add_i32 m0, s65, 0x2000
	v_lshl_add_u64 v[232:233], s[58:59], 0, v[128:129]
	global_load_lds_dwordx4 v[230:231], off
	v_lshl_add_u64 v[234:235], s[58:59], 0, v[132:133]
	s_cbranch_vccnz .Llw642bw1
	s_waitcnt vmcnt(6)
.Llw642bw1:
	s_waitcnt lgkmcnt(0)
	s_barrier
	s_setprio 1
	s_waitcnt lgkmcnt(0)
	v_mfma_f32_16x16x32_bf16 v[60:63], v[146:149], v[186:189], v[60:63]
	v_mfma_f32_16x16x32_bf16 v[56:59], v[160:163], v[186:189], v[56:59]
	v_mfma_f32_16x16x32_bf16 v[44:47], v[146:149], v[194:197], v[44:47]
	v_mfma_f32_16x16x32_bf16 v[40:43], v[160:163], v[194:197], v[40:43]
	v_mfma_f32_16x16x32_bf16 v[28:31], v[146:149], v[202:205], v[28:31]
	v_mfma_f32_16x16x32_bf16 v[24:27], v[160:163], v[202:205], v[24:27]
	v_mfma_f32_16x16x32_bf16 v[12:15], v[146:149], v[210:213], v[12:15]
	v_mfma_f32_16x16x32_bf16 v[8:11], v[160:163], v[210:213], v[8:11]
	v_mfma_f32_16x16x32_bf16 v[60:63], v[156:159], v[190:193], v[60:63]
	v_mfma_f32_16x16x32_bf16 v[56:59], v[164:167], v[190:193], v[56:59]
	v_mfma_f32_16x16x32_bf16 v[44:47], v[156:159], v[198:201], v[44:47]
	v_mfma_f32_16x16x32_bf16 v[40:43], v[164:167], v[198:201], v[40:43]
	v_mfma_f32_16x16x32_bf16 v[28:31], v[156:159], v[206:209], v[28:31]
	v_mfma_f32_16x16x32_bf16 v[24:27], v[164:167], v[206:209], v[24:27]
	v_mfma_f32_16x16x32_bf16 v[12:15], v[156:159], v[214:217], v[12:15]
	v_mfma_f32_16x16x32_bf16 v[8:11], v[164:167], v[214:217], v[8:11]
	s_setprio 0
	s_setprio 1
	v_mfma_f32_16x16x32_bf16 v[52:55], v[168:171], v[186:189], v[52:55]
	v_mfma_f32_16x16x32_bf16 v[48:51], v[176:179], v[186:189], v[48:51]
	v_mfma_f32_16x16x32_bf16 v[36:39], v[168:171], v[194:197], v[36:39]
	v_mfma_f32_16x16x32_bf16 v[32:35], v[176:179], v[194:197], v[32:35]
	v_mfma_f32_16x16x32_bf16 v[20:23], v[168:171], v[202:205], v[20:23]
	v_mfma_f32_16x16x32_bf16 v[16:19], v[176:179], v[202:205], v[16:19]
	v_mfma_f32_16x16x32_bf16 v[4:7], v[168:171], v[210:213], v[4:7]
	v_mfma_f32_16x16x32_bf16 v[0:3], v[176:179], v[210:213], v[0:3]
	v_mfma_f32_16x16x32_bf16 v[52:55], v[172:175], v[190:193], v[52:55]
	v_mfma_f32_16x16x32_bf16 v[48:51], v[180:183], v[190:193], v[48:51]
	v_mfma_f32_16x16x32_bf16 v[36:39], v[172:175], v[198:201], v[36:39]
	v_mfma_f32_16x16x32_bf16 v[32:35], v[180:183], v[198:201], v[32:35]
	v_mfma_f32_16x16x32_bf16 v[20:23], v[172:175], v[206:209], v[20:23]
	v_mfma_f32_16x16x32_bf16 v[16:19], v[180:183], v[206:209], v[16:19]
	v_mfma_f32_16x16x32_bf16 v[4:7], v[172:175], v[214:217], v[4:7]
	v_mfma_f32_16x16x32_bf16 v[0:3], v[180:183], v[214:217], v[0:3]
	s_setprio 0
	s_waitcnt vmcnt(6)
	s_barrier
	s_add_i32 s65, 0, 0x18000
	v_add_u32_e32 v136, s65, v151
	s_add_i32 s66, 0, 0x1c000
	ds_read_b128 v[146:149], v136
	ds_read_b128 v[156:159], v136 offset:1024
	ds_read_b128 v[160:163], v136 offset:2048
	ds_read_b128 v[164:167], v136 offset:3072
	v_add_u32_e32 v136, s66, v151
	ds_read_b128 v[168:171], v136
	ds_read_b128 v[172:175], v136 offset:1024
	ds_read_b128 v[176:179], v136 offset:2048
	ds_read_b128 v[180:183], v136 offset:3072
	s_add_u32 s58, s58, s18
	s_addc_u32 s59, s59, s19
	s_mov_b32 m0, s3
	s_nop 0
	global_load_lds_dwordx4 v[232:233], off
	s_mov_b32 m0, s28
	s_nop 0
	global_load_lds_dwordx4 v[234:235], off
	s_mov_b32 m0, s33
	v_lshl_add_u64 v[236:237], s[58:59], 0, v[128:129]
	ds_read_b128 v[186:189], v155 offset:32768
	ds_read_b128 v[190:193], v155 offset:33792
	ds_read_b128 v[194:197], v155 offset:34816
	ds_read_b128 v[198:201], v155 offset:35840
	ds_read_b128 v[202:205], v155 offset:36864
	ds_read_b128 v[206:209], v155 offset:37888
	ds_read_b128 v[210:213], v155 offset:38912
	ds_read_b128 v[214:217], v155 offset:39936
	global_load_lds_dwordx4 v[236:237], off
	v_lshl_add_u64 v[236:237], s[58:59], 0, v[132:133]
	s_mov_b32 m0, s44
	s_nop 0
	global_load_lds_dwordx4 v[236:237], off
	s_cbranch_vccnz .Llw642bw2
	s_waitcnt vmcnt(8)

.Llw642bw3:
	s_waitcnt lgkmcnt(0)
	s_barrier
	s_setprio 1
	s_waitcnt lgkmcnt(0)
	v_mfma_f32_16x16x32_bf16 v[60:63], v[146:149], v[186:189], v[60:63]
	v_mfma_f32_16x16x32_bf16 v[56:59], v[160:163], v[186:189], v[56:59]
	v_mfma_f32_16x16x32_bf16 v[44:47], v[146:149], v[194:197], v[44:47]
	v_mfma_f32_16x16x32_bf16 v[40:43], v[160:163], v[194:197], v[40:43]
	v_mfma_f32_16x16x32_bf16 v[28:31], v[146:149], v[202:205], v[28:31]
	v_mfma_f32_16x16x32_bf16 v[24:27], v[160:163], v[202:205], v[24:27]
	v_mfma_f32_16x16x32_bf16 v[12:15], v[146:149], v[210:213], v[12:15]
	v_mfma_f32_16x16x32_bf16 v[8:11], v[160:163], v[210:213], v[8:11]
	v_mfma_f32_16x16x32_bf16 v[60:63], v[156:159], v[190:193], v[60:63]
	v_mfma_f32_16x16x32_bf16 v[56:59], v[164:167], v[190:193], v[56:59]
	v_mfma_f32_16x16x32_bf16 v[44:47], v[156:159], v[198:201], v[44:47]
	v_mfma_f32_16x16x32_bf16 v[40:43], v[164:167], v[198:201], v[40:43]
	v_mfma_f32_16x16x32_bf16 v[28:31], v[156:159], v[206:209], v[28:31]
	v_mfma_f32_16x16x32_bf16 v[24:27], v[164:167], v[206:209], v[24:27]
	v_mfma_f32_16x16x32_bf16 v[12:15], v[156:159], v[214:217], v[12:15]
	v_mfma_f32_16x16x32_bf16 v[8:11], v[164:167], v[214:217], v[8:11]
	s_setprio 0
	s_setprio 1
	v_mfma_f32_16x16x32_bf16 v[52:55], v[168:171], v[186:189], v[52:55]
	v_mfma_f32_16x16x32_bf16 v[48:51], v[176:179], v[186:189], v[48:51]
	v_mfma_f32_16x16x32_bf16 v[36:39], v[168:171], v[194:197], v[36:39]
	v_mfma_f32_16x16x32_bf16 v[32:35], v[176:179], v[194:197], v[32:35]
	v_mfma_f32_16x16x32_bf16 v[20:23], v[168:171], v[202:205], v[20:23]
	v_mfma_f32_16x16x32_bf16 v[16:19], v[176:179], v[202:205], v[16:19]
	v_mfma_f32_16x16x32_bf16 v[4:7], v[168:171], v[210:213], v[4:7]
	v_mfma_f32_16x16x32_bf16 v[0:3], v[176:179], v[210:213], v[0:3]
	v_mfma_f32_16x16x32_bf16 v[52:55], v[172:175], v[190:193], v[52:55]
	v_mfma_f32_16x16x32_bf16 v[48:51], v[180:183], v[190:193], v[48:51]
	v_mfma_f32_16x16x32_bf16 v[36:39], v[172:175], v[198:201], v[36:39]
	v_mfma_f32_16x16x32_bf16 v[32:35], v[180:183], v[198:201], v[32:35]
	v_mfma_f32_16x16x32_bf16 v[20:23], v[172:175], v[206:209], v[20:23]
	v_mfma_f32_16x16x32_bf16 v[16:19], v[180:183], v[206:209], v[16:19]
	v_mfma_f32_16x16x32_bf16 v[4:7], v[172:175], v[214:217], v[4:7]
	v_mfma_f32_16x16x32_bf16 v[0:3], v[180:183], v[214:217], v[0:3]
	s_setprio 0
	s_waitcnt vmcnt(6)
	s_barrier
	s_add_u32 s56, s56, 0x100
	s_addc_u32 s57, s57, 0
	s_add_u32 s62, s62, 0x100
	s_addc_u32 s63, s63, 0
	s_cmp_ge_i32 s64, s45
	s_mov_b32 s58, s64
	s_cbranch_scc0 .LBB0_642
	s_branch .LBB0_643

.LBB0_677:
	s_andn2_b64 vcc, exec, s[42:43]
	s_cbranch_vccnz .Lzx679
	s_add_u32 s58, s58, 0x80
	s_addc_u32 s59, s59, 0
	s_add_u32 s71, s60, 0x100
	s_addc_u32 s78, s61, 0
	s_mov_b32 s60, 0
	s_and_b64 vcc, exec, s[94:95]
	ds_read_b128 v[150:153], v147
	ds_read_b128 v[154:157], v147 offset:1024
	ds_read_b128 v[158:161], v147 offset:2048
	ds_read_b128 v[162:165], v147 offset:3072
	ds_read_b128 v[166:169], v148
	ds_read_b128 v[170:173], v148 offset:1024
	ds_read_b128 v[174:177], v148 offset:2048
	ds_read_b128 v[178:181], v148 offset:3072
	s_add_i32 s79, s60, 2
	s_add_u32 s80, s58, 0x80
	s_addc_u32 s61, s59, 0
	s_cmp_eq_u32 s65, s60
	s_cselect_b32 s60, s4, s80
	s_cselect_b32 s61, s5, s61
	s_cselect_b32 s81, s57, s78
	s_cselect_b32 s80, s56, s71
	v_lshl_add_u64 v[182:183], s[58:59], 0, v[136:137]
	s_add_i32 m0, s45, 0xc000
	ds_read_b128 v[186:189], v149
	ds_read_b128 v[190:193], v149 offset:1024
	ds_read_b128 v[194:197], v149 offset:2048
	ds_read_b128 v[198:201], v149 offset:3072
	ds_read_b128 v[202:205], v149 offset:4096
	ds_read_b128 v[206:209], v149 offset:5120
	ds_read_b128 v[210:213], v149 offset:6144
	ds_read_b128 v[214:217], v149 offset:7168
	global_load_lds_dwordx4 v[182:183], off
	v_lshl_add_u64 v[182:183], s[58:59], 0, v[138:139]
	s_add_i32 m0, s45, 0xe000
	s_nop 0
	global_load_lds_dwordx4 v[182:183], off
	s_cbranch_vccnz .Llw679pw0
	s_waitcnt vmcnt(8)
.Llw679pw0:
	s_waitcnt lgkmcnt(0)
	s_barrier
	s_setprio 1
	s_waitcnt lgkmcnt(0)
	v_mfma_f32_16x16x32_bf16 v[120:123], v[150:153], v[186:189], 0
	v_mfma_f32_16x16x32_bf16 v[124:127], v[158:161], v[186:189], 0
	v_mfma_f32_16x16x32_bf16 v[108:111], v[150:153], v[194:197], 0
	v_mfma_f32_16x16x32_bf16 v[104:107], v[158:161], v[194:197], 0
	v_mfma_f32_16x16x32_bf16 v[92:95], v[150:153], v[202:205], 0
	v_mfma_f32_16x16x32_bf16 v[88:91], v[158:161], v[202:205], 0
	v_mfma_f32_16x16x32_bf16 v[76:79], v[150:153], v[210:213], 0
	v_mfma_f32_16x16x32_bf16 v[72:75], v[158:161], v[210:213], 0
	v_mfma_f32_16x16x32_bf16 v[120:123], v[154:157], v[190:193], v[120:123]
	v_mfma_f32_16x16x32_bf16 v[124:127], v[162:165], v[190:193], v[124:127]
	v_mfma_f32_16x16x32_bf16 v[108:111], v[154:157], v[198:201], v[108:111]
	v_mfma_f32_16x16x32_bf16 v[104:107], v[162:165], v[198:201], v[104:107]
	v_mfma_f32_16x16x32_bf16 v[92:95], v[154:157], v[206:209], v[92:95]
	v_mfma_f32_16x16x32_bf16 v[88:91], v[162:165], v[206:209], v[88:91]
	v_mfma_f32_16x16x32_bf16 v[76:79], v[154:157], v[214:217], v[76:79]
	v_mfma_f32_16x16x32_bf16 v[72:75], v[162:165], v[214:217], v[72:75]
	s_setprio 0
	s_setprio 1
	v_mfma_f32_16x16x32_bf16 v[116:119], v[166:169], v[186:189], 0
	v_mfma_f32_16x16x32_bf16 v[112:115], v[174:177], v[186:189], 0
	v_mfma_f32_16x16x32_bf16 v[100:103], v[166:169], v[194:197], 0
	v_mfma_f32_16x16x32_bf16 v[96:99], v[174:177], v[194:197], 0
	v_mfma_f32_16x16x32_bf16 v[84:87], v[166:169], v[202:205], 0
	v_mfma_f32_16x16x32_bf16 v[80:83], v[174:177], v[202:205], 0
	v_mfma_f32_16x16x32_bf16 v[68:71], v[166:169], v[210:213], 0
	v_mfma_f32_16x16x32_bf16 v[64:67], v[174:177], v[210:213], 0
	v_mfma_f32_16x16x32_bf16 v[116:119], v[170:173], v[190:193], v[116:119]
	v_mfma_f32_16x16x32_bf16 v[112:115], v[178:181], v[190:193], v[112:115]
	v_mfma_f32_16x16x32_bf16 v[100:103], v[170:173], v[198:201], v[100:103]
	v_mfma_f32_16x16x32_bf16 v[96:99], v[178:181], v[198:201], v[96:99]
	v_mfma_f32_16x16x32_bf16 v[84:87], v[170:173], v[206:209], v[84:87]
	v_mfma_f32_16x16x32_bf16 v[80:83], v[178:181], v[206:209], v[80:83]
	v_mfma_f32_16x16x32_bf16 v[68:71], v[170:173], v[214:217], v[68:71]
	v_mfma_f32_16x16x32_bf16 v[64:67], v[178:181], v[214:217], v[64:67]
	s_setprio 0
	s_waitcnt vmcnt(8)
	s_barrier
	s_add_i32 s82, s66, s31
	v_lshl_add_u64 v[182:183], s[80:81], 0, v[132:133]
	s_mov_b32 m0, s82
	ds_read_b128 v[186:189], v149 offset:16384
	ds_read_b128 v[190:193], v149 offset:17408
	ds_read_b128 v[194:197], v149 offset:18432
	ds_read_b128 v[198:201], v149 offset:19456
	ds_read_b128 v[202:205], v149 offset:20480
	ds_read_b128 v[206:209], v149 offset:21504
	ds_read_b128 v[210:213], v149 offset:22528
	ds_read_b128 v[214:217], v149 offset:23552
	global_load_lds_dwordx4 v[182:183], off
	s_add_i32 m0, s82, 0x2000
	v_lshl_add_u64 v[224:225], s[80:81], 0, v[128:129]
	s_add_u32 s80, s80, s36
	s_addc_u32 s81, s81, s37
	s_add_i32 s82, s67, s31
	global_load_lds_dwordx4 v[224:225], off
	v_lshl_add_u64 v[226:227], s[80:81], 0, v[132:133]
	s_mov_b32 m0, s82
	v_lshl_add_u64 v[228:229], s[80:81], 0, v[128:129]
	global_load_lds_dwordx4 v[226:227], off
	s_add_i32 m0, s82, 0x2000
	v_lshl_add_u64 v[230:231], s[60:61], 0, v[134:135]
	global_load_lds_dwordx4 v[228:229], off
	v_lshl_add_u64 v[232:233], s[60:61], 0, v[130:131]
	s_cbranch_vccnz .Llw679pw1
	s_waitcnt vmcnt(6)
.Llw679pw1:
	s_waitcnt lgkmcnt(0)
	s_barrier
	s_setprio 1
	s_waitcnt lgkmcnt(0)
	v_mfma_f32_16x16x32_bf16 v[60:63], v[150:153], v[186:189], 0
	v_mfma_f32_16x16x32_bf16 v[56:59], v[158:161], v[186:189], 0
	v_mfma_f32_16x16x32_bf16 v[44:47], v[150:153], v[194:197], 0
	v_mfma_f32_16x16x32_bf16 v[40:43], v[158:161], v[194:197], 0
	v_mfma_f32_16x16x32_bf16 v[28:31], v[150:153], v[202:205], 0
	v_mfma_f32_16x16x32_bf16 v[24:27], v[158:161], v[202:205], 0
	v_mfma_f32_16x16x32_bf16 v[12:15], v[150:153], v[210:213], 0
	v_mfma_f32_16x16x32_bf16 v[8:11], v[158:161], v[210:213], 0
	v_mfma_f32_16x16x32_bf16 v[60:63], v[154:157], v[190:193], v[60:63]
	v_mfma_f32_16x16x32_bf16 v[56:59], v[162:165], v[190:193], v[56:59]
	v_mfma_f32_16x16x32_bf16 v[44:47], v[154:157], v[198:201], v[44:47]
	v_mfma_f32_16x16x32_bf16 v[40:43], v[162:165], v[198:201], v[40:43]
	v_mfma_f32_16x16x32_bf16 v[28:31], v[154:157], v[206:209], v[28:31]
	v_mfma_f32_16x16x32_bf16 v[24:27], v[162:165], v[206:209], v[24:27]
	v_mfma_f32_16x16x32_bf16 v[12:15], v[154:157], v[214:217], v[12:15]
	v_mfma_f32_16x16x32_bf16 v[8:11], v[162:165], v[214:217], v[8:11]
	s_setprio 0
	s_setprio 1
	v_mfma_f32_16x16x32_bf16 v[52:55], v[166:169], v[186:189], 0
	v_mfma_f32_16x16x32_bf16 v[48:51], v[174:177], v[186:189], 0
	v_mfma_f32_16x16x32_bf16 v[36:39], v[166:169], v[194:197], 0
	v_mfma_f32_16x16x32_bf16 v[32:35], v[174:177], v[194:197], 0
	v_mfma_f32_16x16x32_bf16 v[20:23], v[166:169], v[202:205], 0
	v_mfma_f32_16x16x32_bf16 v[16:19], v[174:177], v[202:205], 0
	v_mfma_f32_16x16x32_bf16 v[4:7], v[166:169], v[210:213], 0
	v_mfma_f32_16x16x32_bf16 v[0:3], v[174:177], v[210:213], 0
	v_mfma_f32_16x16x32_bf16 v[52:55], v[170:173], v[190:193], v[52:55]
	v_mfma_f32_16x16x32_bf16 v[48:51], v[178:181], v[190:193], v[48:51]
	v_mfma_f32_16x16x32_bf16 v[36:39], v[170:173], v[198:201], v[36:39]
	v_mfma_f32_16x16x32_bf16 v[32:35], v[178:181], v[198:201], v[32:35]
	v_mfma_f32_16x16x32_bf16 v[20:23], v[170:173], v[206:209], v[20:23]
	v_mfma_f32_16x16x32_bf16 v[16:19], v[178:181], v[206:209], v[16:19]
	v_mfma_f32_16x16x32_bf16 v[4:7], v[170:173], v[214:217], v[4:7]
	v_mfma_f32_16x16x32_bf16 v[0:3], v[178:181], v[214:217], v[0:3]
	s_setprio 0
	s_waitcnt vmcnt(6)
	s_barrier
	s_add_i32 s80, 0, 0x18000
	s_add_i32 s81, 0, 0x1c000
	v_add_u32_e32 v162, s80, v145
	v_add_u32_e32 v178, s81, v145
	ds_read_b128 v[150:153], v162
	ds_read_b128 v[154:157], v162 offset:1024
	ds_read_b128 v[158:161], v162 offset:2048
	ds_read_b128 v[162:165], v162 offset:3072
	ds_read_b128 v[166:169], v178
	ds_read_b128 v[170:173], v178 offset:1024
	ds_read_b128 v[174:177], v178 offset:2048
	ds_read_b128 v[178:181], v178 offset:3072
	s_add_u32 s60, s60, s36
	s_addc_u32 s61, s61, s37
	s_mov_b32 m0, s45
	s_nop 0
	global_load_lds_dwordx4 v[230:231], off
	s_mov_b32 m0, s46
	s_nop 0
	global_load_lds_dwordx4 v[232:233], off
	s_mov_b32 m0, s47
	v_lshl_add_u64 v[234:235], s[60:61], 0, v[134:135]
	ds_read_b128 v[186:189], v149 offset:32768
	ds_read_b128 v[190:193], v149 offset:33792
	ds_read_b128 v[194:197], v149 offset:34816
	ds_read_b128 v[198:201], v149 offset:35840
	ds_read_b128 v[202:205], v149 offset:36864
	ds_read_b128 v[206:209], v149 offset:37888
	ds_read_b128 v[210:213], v149 offset:38912
	ds_read_b128 v[214:217], v149 offset:39936
	global_load_lds_dwordx4 v[234:235], off
	v_lshl_add_u64 v[234:235], s[60:61], 0, v[130:131]
	s_mov_b32 m0, s48
	s_nop 0
	global_load_lds_dwordx4 v[234:235], off
	s_cbranch_vccnz .Llw679pw2
	s_waitcnt vmcnt(8)
.Llw679pw2:
	s_waitcnt lgkmcnt(0)
	s_barrier
	s_setprio 1
	s_waitcnt lgkmcnt(0)
	v_mfma_f32_16x16x32_bf16 v[120:123], v[150:153], v[186:189], v[120:123]
	v_mfma_f32_16x16x32_bf16 v[124:127], v[158:161], v[186:189], v[124:127]
	v_mfma_f32_16x16x32_bf16 v[108:111], v[150:153], v[194:197], v[108:111]
	v_mfma_f32_16x16x32_bf16 v[104:107], v[158:161], v[194:197], v[104:107]
	v_mfma_f32_16x16x32_bf16 v[92:95], v[150:153], v[202:205], v[92:95]
	v_mfma_f32_16x16x32_bf16 v[88:91], v[158:161], v[202:205], v[88:91]
	v_mfma_f32_16x16x32_bf16 v[76:79], v[150:153], v[210:213], v[76:79]
	v_mfma_f32_16x16x32_bf16 v[72:75], v[158:161], v[210:213], v[72:75]
	v_mfma_f32_16x16x32_bf16 v[120:123], v[154:157], v[190:193], v[120:123]
	v_mfma_f32_16x16x32_bf16 v[124:127], v[162:165], v[190:193], v[124:127]
	v_mfma_f32_16x16x32_bf16 v[108:111], v[154:157], v[198:201], v[108:111]
	v_mfma_f32_16x16x32_bf16 v[104:107], v[162:165], v[198:201], v[104:107]
	v_mfma_f32_16x16x32_bf16 v[92:95], v[154:157], v[206:209], v[92:95]
	v_mfma_f32_16x16x32_bf16 v[88:91], v[162:165], v[206:209], v[88:91]
	v_mfma_f32_16x16x32_bf16 v[76:79], v[154:157], v[214:217], v[76:79]
	v_mfma_f32_16x16x32_bf16 v[72:75], v[162:165], v[214:217], v[72:75]
	s_setprio 0
	s_setprio 1
	v_mfma_f32_16x16x32_bf16 v[116:119], v[166:169], v[186:189], v[116:119]
	v_mfma_f32_16x16x32_bf16 v[112:115], v[174:177], v[186:189], v[112:115]
	v_mfma_f32_16x16x32_bf16 v[100:103], v[166:169], v[194:197], v[100:103]
	v_mfma_f32_16x16x32_bf16 v[96:99], v[174:177], v[194:197], v[96:99]
	v_mfma_f32_16x16x32_bf16 v[84:87], v[166:169], v[202:205], v[84:87]
	v_mfma_f32_16x16x32_bf16 v[80:83], v[174:177], v[202:205], v[80:83]
	v_mfma_f32_16x16x32_bf16 v[68:71], v[166:169], v[210:213], v[68:71]
	v_mfma_f32_16x16x32_bf16 v[64:67], v[174:177], v[210:213], v[64:67]
	v_mfma_f32_16x16x32_bf16 v[116:119], v[170:173], v[190:193], v[116:119]
	v_mfma_f32_16x16x32_bf16 v[112:115], v[178:181], v[190:193], v[112:115]
	v_mfma_f32_16x16x32_bf16 v[100:103], v[170:173], v[198:201], v[100:103]
	v_mfma_f32_16x16x32_bf16 v[96:99], v[178:181], v[198:201], v[96:99]
	v_mfma_f32_16x16x32_bf16 v[84:87], v[170:173], v[206:209], v[84:87]
	v_mfma_f32_16x16x32_bf16 v[80:83], v[178:181], v[206:209], v[80:83]
	v_mfma_f32_16x16x32_bf16 v[68:71], v[170:173], v[214:217], v[68:71]
	v_mfma_f32_16x16x32_bf16 v[64:67], v[178:181], v[214:217], v[64:67]
	s_setprio 0
	s_waitcnt vmcnt(8)
	s_barrier
	s_add_i32 s60, s80, s31
	v_lshl_add_u64 v[182:183], v[182:183], 0, s[40:41]
	s_mov_b32 m0, s60
	ds_read_b128 v[186:189], v149 offset:49152
	ds_read_b128 v[190:193], v149 offset:50176
	ds_read_b128 v[194:197], v149 offset:51200
	ds_read_b128 v[198:201], v149 offset:52224
	ds_read_b128 v[202:205], v149 offset:53248
	ds_read_b128 v[206:209], v149 offset:54272
	ds_read_b128 v[210:213], v149 offset:55296
	ds_read_b128 v[214:217], v149 offset:56320
	global_load_lds_dwordx4 v[182:183], off
	v_lshl_add_u64 v[182:183], v[224:225], 0, s[40:41]
	s_add_i32 m0, s60, 0x2000
	s_add_i32 s60, s81, s31
	global_load_lds_dwordx4 v[182:183], off
	v_lshl_add_u64 v[182:183], v[226:227], 0, s[40:41]
	s_mov_b32 m0, s60
	s_nop 0
	global_load_lds_dwordx4 v[182:183], off
	v_lshl_add_u64 v[182:183], v[228:229], 0, s[40:41]
	s_add_i32 m0, s60, 0x2000
	s_nop 0
	global_load_lds_dwordx4 v[182:183], off
	s_cbranch_vccnz .Llw679pw3
	s_waitcnt vmcnt(6)
.Llw679pw3:
	s_waitcnt lgkmcnt(0)
	s_barrier
	s_setprio 1
	s_waitcnt lgkmcnt(0)
	v_mfma_f32_16x16x32_bf16 v[60:63], v[150:153], v[186:189], v[60:63]
	v_mfma_f32_16x16x32_bf16 v[56:59], v[158:161], v[186:189], v[56:59]
	v_mfma_f32_16x16x32_bf16 v[44:47], v[150:153], v[194:197], v[44:47]
	v_mfma_f32_16x16x32_bf16 v[40:43], v[158:161], v[194:197], v[40:43]
	v_mfma_f32_16x16x32_bf16 v[28:31], v[150:153], v[202:205], v[28:31]
	v_mfma_f32_16x16x32_bf16 v[24:27], v[158:161], v[202:205], v[24:27]
	v_mfma_f32_16x16x32_bf16 v[12:15], v[150:153], v[210:213], v[12:15]
	v_mfma_f32_16x16x32_bf16 v[8:11], v[158:161], v[210:213], v[8:11]
	v_mfma_f32_16x16x32_bf16 v[60:63], v[154:157], v[190:193], v[60:63]
	v_mfma_f32_16x16x32_bf16 v[56:59], v[162:165], v[190:193], v[56:59]
	v_mfma_f32_16x16x32_bf16 v[44:47], v[154:157], v[198:201], v[44:47]
	v_mfma_f32_16x16x32_bf16 v[40:43], v[162:165], v[198:201], v[40:43]
	v_mfma_f32_16x16x32_bf16 v[28:31], v[154:157], v[206:209], v[28:31]
	v_mfma_f32_16x16x32_bf16 v[24:27], v[162:165], v[206:209], v[24:27]
	v_mfma_f32_16x16x32_bf16 v[12:15], v[154:157], v[214:217], v[12:15]
	v_mfma_f32_16x16x32_bf16 v[8:11], v[162:165], v[214:217], v[8:11]
	s_setprio 0
	s_setprio 1
	v_mfma_f32_16x16x32_bf16 v[52:55], v[166:169], v[186:189], v[52:55]
	v_mfma_f32_16x16x32_bf16 v[48:51], v[174:177], v[186:189], v[48:51]
	v_mfma_f32_16x16x32_bf16 v[36:39], v[166:169], v[194:197], v[36:39]
	v_mfma_f32_16x16x32_bf16 v[32:35], v[174:177], v[194:197], v[32:35]
	v_mfma_f32_16x16x32_bf16 v[20:23], v[166:169], v[202:205], v[20:23]
	v_mfma_f32_16x16x32_bf16 v[16:19], v[174:177], v[202:205], v[16:19]
	v_mfma_f32_16x16x32_bf16 v[4:7], v[166:169], v[210:213], v[4:7]
	v_mfma_f32_16x16x32_bf16 v[0:3], v[174:177], v[210:213], v[0:3]
	v_mfma_f32_16x16x32_bf16 v[52:55], v[170:173], v[190:193], v[52:55]
	v_mfma_f32_16x16x32_bf16 v[48:51], v[178:181], v[190:193], v[48:51]
	v_mfma_f32_16x16x32_bf16 v[36:39], v[170:173], v[198:201], v[36:39]
	v_mfma_f32_16x16x32_bf16 v[32:35], v[178:181], v[198:201], v[32:35]
	v_mfma_f32_16x16x32_bf16 v[20:23], v[170:173], v[206:209], v[20:23]
	v_mfma_f32_16x16x32_bf16 v[16:19], v[178:181], v[206:209], v[16:19]
	v_mfma_f32_16x16x32_bf16 v[4:7], v[170:173], v[214:217], v[4:7]
	v_mfma_f32_16x16x32_bf16 v[0:3], v[178:181], v[214:217], v[0:3]
	s_setprio 0
	s_waitcnt vmcnt(6)
	s_barrier
	s_add_u32 s58, s58, 0x100
	s_addc_u32 s59, s59, 0
	s_add_u32 s71, s71, 0x100
	s_addc_u32 s78, s78, 0
	s_cmp_ge_i32 s79, s49
	s_mov_b32 s60, s79
	s_cbranch_scc1 .LBB0_681
.LBB0_679:
	ds_read_b128 v[150:153], v147
	ds_read_b128 v[154:157], v147 offset:1024
	ds_read_b128 v[158:161], v147 offset:2048
	ds_read_b128 v[162:165], v147 offset:3072
	ds_read_b128 v[166:169], v148
	ds_read_b128 v[170:173], v148 offset:1024
	ds_read_b128 v[174:177], v148 offset:2048
	ds_read_b128 v[178:181], v148 offset:3072
	s_add_i32 s79, s60, 2
	s_add_u32 s80, s58, 0x80
	s_addc_u32 s61, s59, 0
	s_cmp_eq_u32 s65, s60
	s_cselect_b32 s60, s4, s80
	s_cselect_b32 s61, s5, s61
	s_cselect_b32 s81, s57, s78
	s_cselect_b32 s80, s56, s71
	v_lshl_add_u64 v[182:183], v[230:231], 0, s[40:41]
	s_mov_b32 m0, s53
	s_nop 0
	global_load_lds_dwordx4 v[182:183], off
	v_lshl_add_u64 v[182:183], v[232:233], 0, s[40:41]
	s_mov_b32 m0, s64
	s_nop 0
	global_load_lds_dwordx4 v[182:183], off
	v_lshl_add_u64 v[182:183], s[58:59], 0, v[136:137]
	s_add_i32 m0, s45, 0xc000
	ds_read_b128 v[186:189], v149
	ds_read_b128 v[190:193], v149 offset:1024
	ds_read_b128 v[194:197], v149 offset:2048
	ds_read_b128 v[198:201], v149 offset:3072
	ds_read_b128 v[202:205], v149 offset:4096
	ds_read_b128 v[206:209], v149 offset:5120
	ds_read_b128 v[210:213], v149 offset:6144
	ds_read_b128 v[214:217], v149 offset:7168
	global_load_lds_dwordx4 v[182:183], off
	v_lshl_add_u64 v[182:183], s[58:59], 0, v[138:139]
	s_add_i32 m0, s45, 0xe000
	s_nop 0
	global_load_lds_dwordx4 v[182:183], off
	s_cbranch_vccnz .Llw679bw0
	s_waitcnt vmcnt(8)
.Llw679bw0:
	s_waitcnt lgkmcnt(0)
	s_barrier
	s_setprio 1
	s_waitcnt lgkmcnt(0)
	v_mfma_f32_16x16x32_bf16 v[120:123], v[150:153], v[186:189], v[120:123]
	v_mfma_f32_16x16x32_bf16 v[124:127], v[158:161], v[186:189], v[124:127]
	v_mfma_f32_16x16x32_bf16 v[108:111], v[150:153], v[194:197], v[108:111]
	v_mfma_f32_16x16x32_bf16 v[104:107], v[158:161], v[194:197], v[104:107]
	v_mfma_f32_16x16x32_bf16 v[92:95], v[150:153], v[202:205], v[92:95]
	v_mfma_f32_16x16x32_bf16 v[88:91], v[158:161], v[202:205], v[88:91]
	v_mfma_f32_16x16x32_bf16 v[76:79], v[150:153], v[210:213], v[76:79]
	v_mfma_f32_16x16x32_bf16 v[72:75], v[158:161], v[210:213], v[72:75]
	v_mfma_f32_16x16x32_bf16 v[120:123], v[154:157], v[190:193], v[120:123]
	v_mfma_f32_16x16x32_bf16 v[124:127], v[162:165], v[190:193], v[124:127]
	v_mfma_f32_16x16x32_bf16 v[108:111], v[154:157], v[198:201], v[108:111]
	v_mfma_f32_16x16x32_bf16 v[104:107], v[162:165], v[198:201], v[104:107]
	v_mfma_f32_16x16x32_bf16 v[92:95], v[154:157], v[206:209], v[92:95]
	v_mfma_f32_16x16x32_bf16 v[88:91], v[162:165], v[206:209], v[88:91]
	v_mfma_f32_16x16x32_bf16 v[76:79], v[154:157], v[214:217], v[76:79]
	v_mfma_f32_16x16x32_bf16 v[72:75], v[162:165], v[214:217], v[72:75]
	s_setprio 0
	s_setprio 1
	v_mfma_f32_16x16x32_bf16 v[116:119], v[166:169], v[186:189], v[116:119]
	v_mfma_f32_16x16x32_bf16 v[112:115], v[174:177], v[186:189], v[112:115]
	v_mfma_f32_16x16x32_bf16 v[100:103], v[166:169], v[194:197], v[100:103]
	v_mfma_f32_16x16x32_bf16 v[96:99], v[174:177], v[194:197], v[96:99]
	v_mfma_f32_16x16x32_bf16 v[84:87], v[166:169], v[202:205], v[84:87]
	v_mfma_f32_16x16x32_bf16 v[80:83], v[174:177], v[202:205], v[80:83]
	v_mfma_f32_16x16x32_bf16 v[68:71], v[166:169], v[210:213], v[68:71]
	v_mfma_f32_16x16x32_bf16 v[64:67], v[174:177], v[210:213], v[64:67]
	v_mfma_f32_16x16x32_bf16 v[116:119], v[170:173], v[190:193], v[116:119]
	v_mfma_f32_16x16x32_bf16 v[112:115], v[178:181], v[190:193], v[112:115]
	v_mfma_f32_16x16x32_bf16 v[100:103], v[170:173], v[198:201], v[100:103]
	v_mfma_f32_16x16x32_bf16 v[96:99], v[178:181], v[198:201], v[96:99]
	v_mfma_f32_16x16x32_bf16 v[84:87], v[170:173], v[206:209], v[84:87]
	v_mfma_f32_16x16x32_bf16 v[80:83], v[178:181], v[206:209], v[80:83]
	v_mfma_f32_16x16x32_bf16 v[68:71], v[170:173], v[214:217], v[68:71]
	v_mfma_f32_16x16x32_bf16 v[64:67], v[178:181], v[214:217], v[64:67]
	s_setprio 0
	s_waitcnt vmcnt(8)
	s_barrier
	s_add_i32 s82, s66, s31
	v_lshl_add_u64 v[182:183], s[80:81], 0, v[132:133]
	s_mov_b32 m0, s82
	ds_read_b128 v[186:189], v149 offset:16384
	ds_read_b128 v[190:193], v149 offset:17408
	ds_read_b128 v[194:197], v149 offset:18432
	ds_read_b128 v[198:201], v149 offset:19456
	ds_read_b128 v[202:205], v149 offset:20480
	ds_read_b128 v[206:209], v149 offset:21504
	ds_read_b128 v[210:213], v149 offset:22528
	ds_read_b128 v[214:217], v149 offset:23552
	global_load_lds_dwordx4 v[182:183], off
	s_add_i32 m0, s82, 0x2000
	v_lshl_add_u64 v[224:225], s[80:81], 0, v[128:129]
	s_add_u32 s80, s80, s36
	s_addc_u32 s81, s81, s37
	s_add_i32 s82, s67, s31
	global_load_lds_dwordx4 v[224:225], off
	v_lshl_add_u64 v[226:227], s[80:81], 0, v[132:133]
	s_mov_b32 m0, s82
	v_lshl_add_u64 v[228:229], s[80:81], 0, v[128:129]
	global_load_lds_dwordx4 v[226:227], off
	s_add_i32 m0, s82, 0x2000
	v_lshl_add_u64 v[230:231], s[60:61], 0, v[134:135]
	global_load_lds_dwordx4 v[228:229], off
	v_lshl_add_u64 v[232:233], s[60:61], 0, v[130:131]
	s_cbranch_vccnz .Llw679bw1
	s_waitcnt vmcnt(6)
.Llw679bw1:
	s_waitcnt lgkmcnt(0)
	s_barrier
	s_setprio 1
	s_waitcnt lgkmcnt(0)
	v_mfma_f32_16x16x32_bf16 v[60:63], v[150:153], v[186:189], v[60:63]
	v_mfma_f32_16x16x32_bf16 v[56:59], v[158:161], v[186:189], v[56:59]
	v_mfma_f32_16x16x32_bf16 v[44:47], v[150:153], v[194:197], v[44:47]
	v_mfma_f32_16x16x32_bf16 v[40:43], v[158:161], v[194:197], v[40:43]
	v_mfma_f32_16x16x32_bf16 v[28:31], v[150:153], v[202:205], v[28:31]
	v_mfma_f32_16x16x32_bf16 v[24:27], v[158:161], v[202:205], v[24:27]
	v_mfma_f32_16x16x32_bf16 v[12:15], v[150:153], v[210:213], v[12:15]
	v_mfma_f32_16x16x32_bf16 v[8:11], v[158:161], v[210:213], v[8:11]
	v_mfma_f32_16x16x32_bf16 v[60:63], v[154:157], v[190:193], v[60:63]
	v_mfma_f32_16x16x32_bf16 v[56:59], v[162:165], v[190:193], v[56:59]
	v_mfma_f32_16x16x32_bf16 v[44:47], v[154:157], v[198:201], v[44:47]
	v_mfma_f32_16x16x32_bf16 v[40:43], v[162:165], v[198:201], v[40:43]
	v_mfma_f32_16x16x32_bf16 v[28:31], v[154:157], v[206:209], v[28:31]
	v_mfma_f32_16x16x32_bf16 v[24:27], v[162:165], v[206:209], v[24:27]
	v_mfma_f32_16x16x32_bf16 v[12:15], v[154:157], v[214:217], v[12:15]
	v_mfma_f32_16x16x32_bf16 v[8:11], v[162:165], v[214:217], v[8:11]
	s_setprio 0
	s_setprio 1
	v_mfma_f32_16x16x32_bf16 v[52:55], v[166:169], v[186:189], v[52:55]
	v_mfma_f32_16x16x32_bf16 v[48:51], v[174:177], v[186:189], v[48:51]
	v_mfma_f32_16x16x32_bf16 v[36:39], v[166:169], v[194:197], v[36:39]
	v_mfma_f32_16x16x32_bf16 v[32:35], v[174:177], v[194:197], v[32:35]
	v_mfma_f32_16x16x32_bf16 v[20:23], v[166:169], v[202:205], v[20:23]
	v_mfma_f32_16x16x32_bf16 v[16:19], v[174:177], v[202:205], v[16:19]
	v_mfma_f32_16x16x32_bf16 v[4:7], v[166:169], v[210:213], v[4:7]
	v_mfma_f32_16x16x32_bf16 v[0:3], v[174:177], v[210:213], v[0:3]
	v_mfma_f32_16x16x32_bf16 v[52:55], v[170:173], v[190:193], v[52:55]
	v_mfma_f32_16x16x32_bf16 v[48:51], v[178:181], v[190:193], v[48:51]
	v_mfma_f32_16x16x32_bf16 v[36:39], v[170:173], v[198:201], v[36:39]
	v_mfma_f32_16x16x32_bf16 v[32:35], v[178:181], v[198:201], v[32:35]
	v_mfma_f32_16x16x32_bf16 v[20:23], v[170:173], v[206:209], v[20:23]
	v_mfma_f32_16x16x32_bf16 v[16:19], v[178:181], v[206:209], v[16:19]
	v_mfma_f32_16x16x32_bf16 v[4:7], v[170:173], v[214:217], v[4:7]
	v_mfma_f32_16x16x32_bf16 v[0:3], v[178:181], v[214:217], v[0:3]
	s_setprio 0
	s_waitcnt vmcnt(6)
	s_barrier
	s_add_i32 s80, 0, 0x18000
	s_add_i32 s81, 0, 0x1c000
	v_add_u32_e32 v162, s80, v145
	v_add_u32_e32 v178, s81, v145
	ds_read_b128 v[150:153], v162
	ds_read_b128 v[154:157], v162 offset:1024
	ds_read_b128 v[158:161], v162 offset:2048
	ds_read_b128 v[162:165], v162 offset:3072
	ds_read_b128 v[166:169], v178
	ds_read_b128 v[170:173], v178 offset:1024
	ds_read_b128 v[174:177], v178 offset:2048
	ds_read_b128 v[178:181], v178 offset:3072
	s_add_u32 s60, s60, s36
	s_addc_u32 s61, s61, s37
	s_mov_b32 m0, s45
	s_nop 0
	global_load_lds_dwordx4 v[230:231], off
	s_mov_b32 m0, s46
	s_nop 0
	global_load_lds_dwordx4 v[232:233], off
	s_mov_b32 m0, s47
	v_lshl_add_u64 v[234:235], s[60:61], 0, v[134:135]
	ds_read_b128 v[186:189], v149 offset:32768
	ds_read_b128 v[190:193], v149 offset:33792
	ds_read_b128 v[194:197], v149 offset:34816
	ds_read_b128 v[198:201], v149 offset:35840
	ds_read_b128 v[202:205], v149 offset:36864
	ds_read_b128 v[206:209], v149 offset:37888
	ds_read_b128 v[210:213], v149 offset:38912
	ds_read_b128 v[214:217], v149 offset:39936
	global_load_lds_dwordx4 v[234:235], off
	v_lshl_add_u64 v[234:235], s[60:61], 0, v[130:131]
	s_mov_b32 m0, s48
	s_nop 0
	global_load_lds_dwordx4 v[234:235], off
	s_cbranch_vccnz .Llw679bw2
	s_waitcnt vmcnt(8)

.Llw679bw3:
	s_waitcnt lgkmcnt(0)
	s_barrier
	s_setprio 1
	s_waitcnt lgkmcnt(0)
	v_mfma_f32_16x16x32_bf16 v[60:63], v[150:153], v[186:189], v[60:63]
	v_mfma_f32_16x16x32_bf16 v[56:59], v[158:161], v[186:189], v[56:59]
	v_mfma_f32_16x16x32_bf16 v[44:47], v[150:153], v[194:197], v[44:47]
	v_mfma_f32_16x16x32_bf16 v[40:43], v[158:161], v[194:197], v[40:43]
	v_mfma_f32_16x16x32_bf16 v[28:31], v[150:153], v[202:205], v[28:31]
	v_mfma_f32_16x16x32_bf16 v[24:27], v[158:161], v[202:205], v[24:27]
	v_mfma_f32_16x16x32_bf16 v[12:15], v[150:153], v[210:213], v[12:15]
	v_mfma_f32_16x16x32_bf16 v[8:11], v[158:161], v[210:213], v[8:11]
	v_mfma_f32_16x16x32_bf16 v[60:63], v[154:157], v[190:193], v[60:63]
	v_mfma_f32_16x16x32_bf16 v[56:59], v[162:165], v[190:193], v[56:59]
	v_mfma_f32_16x16x32_bf16 v[44:47], v[154:157], v[198:201], v[44:47]
	v_mfma_f32_16x16x32_bf16 v[40:43], v[162:165], v[198:201], v[40:43]
	v_mfma_f32_16x16x32_bf16 v[28:31], v[154:157], v[206:209], v[28:31]
	v_mfma_f32_16x16x32_bf16 v[24:27], v[162:165], v[206:209], v[24:27]
	v_mfma_f32_16x16x32_bf16 v[12:15], v[154:157], v[214:217], v[12:15]
	v_mfma_f32_16x16x32_bf16 v[8:11], v[162:165], v[214:217], v[8:11]
	s_setprio 0
	s_setprio 1
	v_mfma_f32_16x16x32_bf16 v[52:55], v[166:169], v[186:189], v[52:55]
	v_mfma_f32_16x16x32_bf16 v[48:51], v[174:177], v[186:189], v[48:51]
	v_mfma_f32_16x16x32_bf16 v[36:39], v[166:169], v[194:197], v[36:39]
	v_mfma_f32_16x16x32_bf16 v[32:35], v[174:177], v[194:197], v[32:35]
	v_mfma_f32_16x16x32_bf16 v[20:23], v[166:169], v[202:205], v[20:23]
	v_mfma_f32_16x16x32_bf16 v[16:19], v[174:177], v[202:205], v[16:19]
	v_mfma_f32_16x16x32_bf16 v[4:7], v[166:169], v[210:213], v[4:7]
	v_mfma_f32_16x16x32_bf16 v[0:3], v[174:177], v[210:213], v[0:3]
	v_mfma_f32_16x16x32_bf16 v[52:55], v[170:173], v[190:193], v[52:55]
	v_mfma_f32_16x16x32_bf16 v[48:51], v[178:181], v[190:193], v[48:51]
	v_mfma_f32_16x16x32_bf16 v[36:39], v[170:173], v[198:201], v[36:39]
	v_mfma_f32_16x16x32_bf16 v[32:35], v[178:181], v[198:201], v[32:35]
	v_mfma_f32_16x16x32_bf16 v[20:23], v[170:173], v[206:209], v[20:23]
	v_mfma_f32_16x16x32_bf16 v[16:19], v[178:181], v[206:209], v[16:19]
	v_mfma_f32_16x16x32_bf16 v[4:7], v[170:173], v[214:217], v[4:7]
	v_mfma_f32_16x16x32_bf16 v[0:3], v[178:181], v[214:217], v[0:3]
	s_setprio 0
	s_waitcnt vmcnt(6)
	s_barrier
	s_add_u32 s58, s58, 0x100
	s_addc_u32 s59, s59, 0
	s_add_u32 s71, s71, 0x100
	s_addc_u32 s78, s78, 0
	s_cmp_ge_i32 s79, s49
	s_mov_b32 s60, s79
	s_cbranch_scc0 .LBB0_679
	v_readlane_b32 s82, v248, 38
	v_readlane_b32 s83, v248, 39
	s_branch .LBB0_681

.LBB0_919:
	s_and_b64 vcc, exec, s[8:9]
	s_cbranch_vccnz .Lzx921
	s_add_u32 s40, s40, 0x80
	s_addc_u32 s41, s41, 0
	s_add_u32 s61, s42, 0x100
	s_addc_u32 s62, s43, 0
	s_mov_b32 s42, 0
	s_and_b64 vcc, exec, s[94:95]
	ds_read_b128 v[144:147], v153
	ds_read_b128 v[158:161], v153 offset:1024
	ds_read_b128 v[162:165], v153 offset:2048
	ds_read_b128 v[166:169], v153 offset:3072
	ds_read_b128 v[170:173], v154
	ds_read_b128 v[174:177], v154 offset:1024
	ds_read_b128 v[178:181], v154 offset:2048
	ds_read_b128 v[186:189], v154 offset:3072
	s_add_i32 s63, s42, 2
	s_add_u32 s64, s40, 0x80
	s_addc_u32 s43, s41, 0
	s_cmp_eq_u32 s50, s42
	s_cselect_b32 s42, s6, s64
	s_cselect_b32 s43, s7, s43
	s_cselect_b32 s65, s39, s62
	s_cselect_b32 s64, s38, s61
	s_mov_b32 m0, s53
	v_lshl_add_u64 v[148:149], s[40:41], 0, v[136:137]
	ds_read_b128 v[190:193], v155
	ds_read_b128 v[194:197], v155 offset:1024
	ds_read_b128 v[198:201], v155 offset:2048
	ds_read_b128 v[202:205], v155 offset:3072
	ds_read_b128 v[206:209], v155 offset:4096
	ds_read_b128 v[210:213], v155 offset:5120
	ds_read_b128 v[214:217], v155 offset:6144
	ds_read_b128 v[224:227], v155 offset:7168
	global_load_lds_dwordx4 v[148:149], off
	v_lshl_add_u64 v[148:149], s[40:41], 0, v[138:139]
	s_mov_b32 m0, s54
	s_nop 0
	global_load_lds_dwordx4 v[148:149], off
	s_cbranch_vccnz .Llw921pw0
	s_waitcnt vmcnt(8)
.Llw921pw0:
	s_waitcnt lgkmcnt(0)
	s_barrier
	s_setprio 1
	s_waitcnt lgkmcnt(0)
	v_mfma_f32_16x16x32_bf16 v[120:123], v[144:147], v[190:193], 0
	v_mfma_f32_16x16x32_bf16 v[116:119], v[162:165], v[190:193], 0
	v_mfma_f32_16x16x32_bf16 v[108:111], v[144:147], v[198:201], 0
	v_mfma_f32_16x16x32_bf16 v[100:103], v[162:165], v[198:201], 0
	v_mfma_f32_16x16x32_bf16 v[92:95], v[144:147], v[206:209], 0
	v_mfma_f32_16x16x32_bf16 v[84:87], v[162:165], v[206:209], 0
	v_mfma_f32_16x16x32_bf16 v[76:79], v[144:147], v[214:217], 0
	v_mfma_f32_16x16x32_bf16 v[68:71], v[162:165], v[214:217], 0
	v_mfma_f32_16x16x32_bf16 v[120:123], v[158:161], v[194:197], v[120:123]
	v_mfma_f32_16x16x32_bf16 v[116:119], v[166:169], v[194:197], v[116:119]
	v_mfma_f32_16x16x32_bf16 v[108:111], v[158:161], v[202:205], v[108:111]
	v_mfma_f32_16x16x32_bf16 v[100:103], v[166:169], v[202:205], v[100:103]
	v_mfma_f32_16x16x32_bf16 v[92:95], v[158:161], v[210:213], v[92:95]
	v_mfma_f32_16x16x32_bf16 v[84:87], v[166:169], v[210:213], v[84:87]
	v_mfma_f32_16x16x32_bf16 v[76:79], v[158:161], v[224:227], v[76:79]
	v_mfma_f32_16x16x32_bf16 v[68:71], v[166:169], v[224:227], v[68:71]
	s_setprio 0
	s_setprio 1
	v_mfma_f32_16x16x32_bf16 v[124:127], v[170:173], v[190:193], 0
	v_mfma_f32_16x16x32_bf16 v[112:115], v[178:181], v[190:193], 0
	v_mfma_f32_16x16x32_bf16 v[104:107], v[170:173], v[198:201], 0
	v_mfma_f32_16x16x32_bf16 v[96:99], v[178:181], v[198:201], 0
	v_mfma_f32_16x16x32_bf16 v[88:91], v[170:173], v[206:209], 0
	v_mfma_f32_16x16x32_bf16 v[80:83], v[178:181], v[206:209], 0
	v_mfma_f32_16x16x32_bf16 v[72:75], v[170:173], v[214:217], 0
	v_mfma_f32_16x16x32_bf16 v[64:67], v[178:181], v[214:217], 0
	v_mfma_f32_16x16x32_bf16 v[124:127], v[174:177], v[194:197], v[124:127]
	v_mfma_f32_16x16x32_bf16 v[112:115], v[186:189], v[194:197], v[112:115]
	v_mfma_f32_16x16x32_bf16 v[104:107], v[174:177], v[202:205], v[104:107]
	v_mfma_f32_16x16x32_bf16 v[96:99], v[186:189], v[202:205], v[96:99]
	v_mfma_f32_16x16x32_bf16 v[88:91], v[174:177], v[210:213], v[88:91]
	v_mfma_f32_16x16x32_bf16 v[80:83], v[186:189], v[210:213], v[80:83]
	v_mfma_f32_16x16x32_bf16 v[72:75], v[174:177], v[224:227], v[72:75]
	v_mfma_f32_16x16x32_bf16 v[64:67], v[186:189], v[224:227], v[64:67]
	s_setprio 0
	s_waitcnt vmcnt(8)
	s_barrier
	s_mov_b32 m0, s55
	v_lshl_add_u64 v[148:149], s[64:65], 0, v[132:133]
	v_lshl_add_u64 v[182:183], s[64:65], 0, v[128:129]
	s_add_u32 s64, s64, s16
	ds_read_b128 v[190:193], v155 offset:16384
	ds_read_b128 v[194:197], v155 offset:17408
	ds_read_b128 v[198:201], v155 offset:18432
	ds_read_b128 v[202:205], v155 offset:19456
	ds_read_b128 v[206:209], v155 offset:20480
	ds_read_b128 v[210:213], v155 offset:21504
	ds_read_b128 v[214:217], v155 offset:22528
	ds_read_b128 v[224:227], v155 offset:23552
	global_load_lds_dwordx4 v[148:149], off
	s_mov_b32 m0, s56
	s_addc_u32 s65, s65, s17
	s_add_i32 s66, s51, s31
	global_load_lds_dwordx4 v[182:183], off
	v_lshl_add_u64 v[228:229], s[64:65], 0, v[132:133]
	s_mov_b32 m0, s66
	v_lshl_add_u64 v[230:231], s[64:65], 0, v[128:129]
	global_load_lds_dwordx4 v[228:229], off
	s_add_i32 m0, s66, 0x2000
	v_lshl_add_u64 v[232:233], s[42:43], 0, v[134:135]
	global_load_lds_dwordx4 v[230:231], off
	v_lshl_add_u64 v[234:235], s[42:43], 0, v[130:131]
	s_cbranch_vccnz .Llw921pw1
	s_waitcnt vmcnt(6)
.Llw921pw1:
	s_waitcnt lgkmcnt(0)
	s_barrier
	s_setprio 1
	s_waitcnt lgkmcnt(0)
	v_mfma_f32_16x16x32_bf16 v[60:63], v[144:147], v[190:193], 0
	v_mfma_f32_16x16x32_bf16 v[52:55], v[162:165], v[190:193], 0
	v_mfma_f32_16x16x32_bf16 v[44:47], v[144:147], v[198:201], 0
	v_mfma_f32_16x16x32_bf16 v[36:39], v[162:165], v[198:201], 0
	v_mfma_f32_16x16x32_bf16 v[28:31], v[144:147], v[206:209], 0
	v_mfma_f32_16x16x32_bf16 v[20:23], v[162:165], v[206:209], 0
	v_mfma_f32_16x16x32_bf16 v[12:15], v[144:147], v[214:217], 0
	v_mfma_f32_16x16x32_bf16 v[4:7], v[162:165], v[214:217], 0
	v_mfma_f32_16x16x32_bf16 v[60:63], v[158:161], v[194:197], v[60:63]
	v_mfma_f32_16x16x32_bf16 v[52:55], v[166:169], v[194:197], v[52:55]
	v_mfma_f32_16x16x32_bf16 v[44:47], v[158:161], v[202:205], v[44:47]
	v_mfma_f32_16x16x32_bf16 v[36:39], v[166:169], v[202:205], v[36:39]
	v_mfma_f32_16x16x32_bf16 v[28:31], v[158:161], v[210:213], v[28:31]
	v_mfma_f32_16x16x32_bf16 v[20:23], v[166:169], v[210:213], v[20:23]
	v_mfma_f32_16x16x32_bf16 v[12:15], v[158:161], v[224:227], v[12:15]
	v_mfma_f32_16x16x32_bf16 v[4:7], v[166:169], v[224:227], v[4:7]
	s_setprio 0
	s_setprio 1
	v_mfma_f32_16x16x32_bf16 v[56:59], v[170:173], v[190:193], 0
	v_mfma_f32_16x16x32_bf16 v[48:51], v[178:181], v[190:193], 0
	v_mfma_f32_16x16x32_bf16 v[40:43], v[170:173], v[198:201], 0
	v_mfma_f32_16x16x32_bf16 v[32:35], v[178:181], v[198:201], 0
	v_mfma_f32_16x16x32_bf16 v[24:27], v[170:173], v[206:209], 0
	v_mfma_f32_16x16x32_bf16 v[16:19], v[178:181], v[206:209], 0
	v_mfma_f32_16x16x32_bf16 v[8:11], v[170:173], v[214:217], 0
	v_mfma_f32_16x16x32_bf16 v[0:3], v[178:181], v[214:217], 0
	v_mfma_f32_16x16x32_bf16 v[56:59], v[174:177], v[194:197], v[56:59]
	v_mfma_f32_16x16x32_bf16 v[48:51], v[186:189], v[194:197], v[48:51]
	v_mfma_f32_16x16x32_bf16 v[40:43], v[174:177], v[202:205], v[40:43]
	v_mfma_f32_16x16x32_bf16 v[32:35], v[186:189], v[202:205], v[32:35]
	v_mfma_f32_16x16x32_bf16 v[24:27], v[174:177], v[210:213], v[24:27]
	v_mfma_f32_16x16x32_bf16 v[16:19], v[186:189], v[210:213], v[16:19]
	v_mfma_f32_16x16x32_bf16 v[8:11], v[174:177], v[224:227], v[8:11]
	v_mfma_f32_16x16x32_bf16 v[0:3], v[186:189], v[224:227], v[0:3]
	s_setprio 0
	s_waitcnt vmcnt(6)
	s_barrier
	s_add_i32 s64, 0, 0x18000
	v_add_u32_e32 v157, s64, v151
	s_add_i32 s65, 0, 0x1c000
	ds_read_b128 v[144:147], v157
	ds_read_b128 v[158:161], v157 offset:1024
	ds_read_b128 v[162:165], v157 offset:2048
	ds_read_b128 v[166:169], v157 offset:3072
	v_add_u32_e32 v157, s65, v151
	ds_read_b128 v[170:173], v157
	ds_read_b128 v[174:177], v157 offset:1024
	ds_read_b128 v[178:181], v157 offset:2048
	ds_read_b128 v[186:189], v157 offset:3072
	s_add_u32 s42, s42, s16
	s_addc_u32 s43, s43, s17
	s_mov_b32 m0, s28
	s_nop 0
	global_load_lds_dwordx4 v[232:233], off
	s_mov_b32 m0, s33
	s_nop 0
	global_load_lds_dwordx4 v[234:235], off
	s_mov_b32 m0, s44
	v_lshl_add_u64 v[236:237], s[42:43], 0, v[134:135]
	ds_read_b128 v[190:193], v155 offset:32768
	ds_read_b128 v[194:197], v155 offset:33792
	ds_read_b128 v[198:201], v155 offset:34816
	ds_read_b128 v[202:205], v155 offset:35840
	ds_read_b128 v[206:209], v155 offset:36864
	ds_read_b128 v[210:213], v155 offset:37888
	ds_read_b128 v[214:217], v155 offset:38912
	ds_read_b128 v[224:227], v155 offset:39936
	global_load_lds_dwordx4 v[236:237], off
	v_lshl_add_u64 v[236:237], s[42:43], 0, v[130:131]
	s_mov_b32 m0, s45
	s_nop 0
	global_load_lds_dwordx4 v[236:237], off
	s_cbranch_vccnz .Llw921pw2
	s_waitcnt vmcnt(8)
.Llw921pw2:
	s_waitcnt lgkmcnt(0)
	s_barrier
	s_setprio 1
	s_waitcnt lgkmcnt(0)
	v_mfma_f32_16x16x32_bf16 v[120:123], v[144:147], v[190:193], v[120:123]
	v_mfma_f32_16x16x32_bf16 v[116:119], v[162:165], v[190:193], v[116:119]
	v_mfma_f32_16x16x32_bf16 v[108:111], v[144:147], v[198:201], v[108:111]
	v_mfma_f32_16x16x32_bf16 v[100:103], v[162:165], v[198:201], v[100:103]
	v_mfma_f32_16x16x32_bf16 v[92:95], v[144:147], v[206:209], v[92:95]
	v_mfma_f32_16x16x32_bf16 v[84:87], v[162:165], v[206:209], v[84:87]
	v_mfma_f32_16x16x32_bf16 v[76:79], v[144:147], v[214:217], v[76:79]
	v_mfma_f32_16x16x32_bf16 v[68:71], v[162:165], v[214:217], v[68:71]
	v_mfma_f32_16x16x32_bf16 v[120:123], v[158:161], v[194:197], v[120:123]
	v_mfma_f32_16x16x32_bf16 v[116:119], v[166:169], v[194:197], v[116:119]
	v_mfma_f32_16x16x32_bf16 v[108:111], v[158:161], v[202:205], v[108:111]
	v_mfma_f32_16x16x32_bf16 v[100:103], v[166:169], v[202:205], v[100:103]
	v_mfma_f32_16x16x32_bf16 v[92:95], v[158:161], v[210:213], v[92:95]
	v_mfma_f32_16x16x32_bf16 v[84:87], v[166:169], v[210:213], v[84:87]
	v_mfma_f32_16x16x32_bf16 v[76:79], v[158:161], v[224:227], v[76:79]
	v_mfma_f32_16x16x32_bf16 v[68:71], v[166:169], v[224:227], v[68:71]
	s_setprio 0
	s_setprio 1
	v_mfma_f32_16x16x32_bf16 v[124:127], v[170:173], v[190:193], v[124:127]
	v_mfma_f32_16x16x32_bf16 v[112:115], v[178:181], v[190:193], v[112:115]
	v_mfma_f32_16x16x32_bf16 v[104:107], v[170:173], v[198:201], v[104:107]
	v_mfma_f32_16x16x32_bf16 v[96:99], v[178:181], v[198:201], v[96:99]
	v_mfma_f32_16x16x32_bf16 v[88:91], v[170:173], v[206:209], v[88:91]
	v_mfma_f32_16x16x32_bf16 v[80:83], v[178:181], v[206:209], v[80:83]
	v_mfma_f32_16x16x32_bf16 v[72:75], v[170:173], v[214:217], v[72:75]
	v_mfma_f32_16x16x32_bf16 v[64:67], v[178:181], v[214:217], v[64:67]
	v_mfma_f32_16x16x32_bf16 v[124:127], v[174:177], v[194:197], v[124:127]
	v_mfma_f32_16x16x32_bf16 v[112:115], v[186:189], v[194:197], v[112:115]
	v_mfma_f32_16x16x32_bf16 v[104:107], v[174:177], v[202:205], v[104:107]
	v_mfma_f32_16x16x32_bf16 v[96:99], v[186:189], v[202:205], v[96:99]
	v_mfma_f32_16x16x32_bf16 v[88:91], v[174:177], v[210:213], v[88:91]
	v_mfma_f32_16x16x32_bf16 v[80:83], v[186:189], v[210:213], v[80:83]
	v_mfma_f32_16x16x32_bf16 v[72:75], v[174:177], v[224:227], v[72:75]
	v_mfma_f32_16x16x32_bf16 v[64:67], v[186:189], v[224:227], v[64:67]
	s_setprio 0
	s_waitcnt vmcnt(8)
	s_barrier
	s_add_i32 s42, s64, s31
	v_lshl_add_u64 v[148:149], v[148:149], 0, s[36:37]
	s_mov_b32 m0, s42
	ds_read_b128 v[190:193], v155 offset:49152
	ds_read_b128 v[194:197], v155 offset:50176
	ds_read_b128 v[198:201], v155 offset:51200
	ds_read_b128 v[202:205], v155 offset:52224
	ds_read_b128 v[206:209], v155 offset:53248
	ds_read_b128 v[210:213], v155 offset:54272
	ds_read_b128 v[214:217], v155 offset:55296
	ds_read_b128 v[224:227], v155 offset:56320
	global_load_lds_dwordx4 v[148:149], off
	v_lshl_add_u64 v[148:149], v[182:183], 0, s[36:37]
	s_add_i32 m0, s42, 0x2000
	s_add_i32 s42, s65, s31
	global_load_lds_dwordx4 v[148:149], off
	v_lshl_add_u64 v[148:149], v[228:229], 0, s[36:37]
	s_mov_b32 m0, s42
	s_nop 0
	global_load_lds_dwordx4 v[148:149], off
	v_lshl_add_u64 v[148:149], v[230:231], 0, s[36:37]
	s_add_i32 m0, s42, 0x2000
	s_nop 0
	global_load_lds_dwordx4 v[148:149], off
	s_cbranch_vccnz .Llw921pw3
	s_waitcnt vmcnt(6)
.Llw921pw3:
	s_waitcnt lgkmcnt(0)
	s_barrier
	s_setprio 1
	s_waitcnt lgkmcnt(0)
	v_mfma_f32_16x16x32_bf16 v[60:63], v[144:147], v[190:193], v[60:63]
	v_mfma_f32_16x16x32_bf16 v[52:55], v[162:165], v[190:193], v[52:55]
	v_mfma_f32_16x16x32_bf16 v[44:47], v[144:147], v[198:201], v[44:47]
	v_mfma_f32_16x16x32_bf16 v[36:39], v[162:165], v[198:201], v[36:39]
	v_mfma_f32_16x16x32_bf16 v[28:31], v[144:147], v[206:209], v[28:31]
	v_mfma_f32_16x16x32_bf16 v[20:23], v[162:165], v[206:209], v[20:23]
	v_mfma_f32_16x16x32_bf16 v[12:15], v[144:147], v[214:217], v[12:15]
	v_mfma_f32_16x16x32_bf16 v[4:7], v[162:165], v[214:217], v[4:7]
	v_mfma_f32_16x16x32_bf16 v[60:63], v[158:161], v[194:197], v[60:63]
	v_mfma_f32_16x16x32_bf16 v[52:55], v[166:169], v[194:197], v[52:55]
	v_mfma_f32_16x16x32_bf16 v[44:47], v[158:161], v[202:205], v[44:47]
	v_mfma_f32_16x16x32_bf16 v[36:39], v[166:169], v[202:205], v[36:39]
	v_mfma_f32_16x16x32_bf16 v[28:31], v[158:161], v[210:213], v[28:31]
	v_mfma_f32_16x16x32_bf16 v[20:23], v[166:169], v[210:213], v[20:23]
	v_mfma_f32_16x16x32_bf16 v[12:15], v[158:161], v[224:227], v[12:15]
	v_mfma_f32_16x16x32_bf16 v[4:7], v[166:169], v[224:227], v[4:7]
	s_setprio 0
	s_setprio 1
	v_mfma_f32_16x16x32_bf16 v[56:59], v[170:173], v[190:193], v[56:59]
	v_mfma_f32_16x16x32_bf16 v[48:51], v[178:181], v[190:193], v[48:51]
	v_mfma_f32_16x16x32_bf16 v[40:43], v[170:173], v[198:201], v[40:43]
	v_mfma_f32_16x16x32_bf16 v[32:35], v[178:181], v[198:201], v[32:35]
	v_mfma_f32_16x16x32_bf16 v[24:27], v[170:173], v[206:209], v[24:27]
	v_mfma_f32_16x16x32_bf16 v[16:19], v[178:181], v[206:209], v[16:19]
	v_mfma_f32_16x16x32_bf16 v[8:11], v[170:173], v[214:217], v[8:11]
	v_mfma_f32_16x16x32_bf16 v[0:3], v[178:181], v[214:217], v[0:3]
	v_mfma_f32_16x16x32_bf16 v[56:59], v[174:177], v[194:197], v[56:59]
	v_mfma_f32_16x16x32_bf16 v[48:51], v[186:189], v[194:197], v[48:51]
	v_mfma_f32_16x16x32_bf16 v[40:43], v[174:177], v[202:205], v[40:43]
	v_mfma_f32_16x16x32_bf16 v[32:35], v[186:189], v[202:205], v[32:35]
	v_mfma_f32_16x16x32_bf16 v[24:27], v[174:177], v[210:213], v[24:27]
	v_mfma_f32_16x16x32_bf16 v[16:19], v[186:189], v[210:213], v[16:19]
	v_mfma_f32_16x16x32_bf16 v[8:11], v[174:177], v[224:227], v[8:11]
	v_mfma_f32_16x16x32_bf16 v[0:3], v[186:189], v[224:227], v[0:3]
	s_setprio 0
	s_waitcnt vmcnt(6)
	s_barrier
	s_add_u32 s40, s40, 0x100
	s_addc_u32 s41, s41, 0
	s_add_u32 s61, s61, 0x100
	s_addc_u32 s62, s62, 0
	s_cmp_ge_i32 s63, s49
	s_mov_b32 s42, s63
	s_cbranch_scc1 .LBB0_922
.LBB0_921:
	ds_read_b128 v[144:147], v153
	ds_read_b128 v[158:161], v153 offset:1024
	ds_read_b128 v[162:165], v153 offset:2048
	ds_read_b128 v[166:169], v153 offset:3072
	ds_read_b128 v[170:173], v154
	ds_read_b128 v[174:177], v154 offset:1024
	ds_read_b128 v[178:181], v154 offset:2048
	ds_read_b128 v[186:189], v154 offset:3072
	s_add_i32 s63, s42, 2
	s_add_u32 s64, s40, 0x80
	s_addc_u32 s43, s41, 0
	s_cmp_eq_u32 s50, s42
	s_cselect_b32 s42, s6, s64
	s_cselect_b32 s43, s7, s43
	s_cselect_b32 s65, s39, s62
	s_cselect_b32 s64, s38, s61
	v_lshl_add_u64 v[148:149], v[232:233], 0, s[36:37]
	s_mov_b32 m0, s47
	s_nop 0
	global_load_lds_dwordx4 v[148:149], off
	v_lshl_add_u64 v[148:149], v[234:235], 0, s[36:37]
	s_mov_b32 m0, s48
	s_nop 0
	global_load_lds_dwordx4 v[148:149], off
	s_mov_b32 m0, s53
	v_lshl_add_u64 v[148:149], s[40:41], 0, v[136:137]
	ds_read_b128 v[190:193], v155
	ds_read_b128 v[194:197], v155 offset:1024
	ds_read_b128 v[198:201], v155 offset:2048
	ds_read_b128 v[202:205], v155 offset:3072
	ds_read_b128 v[206:209], v155 offset:4096
	ds_read_b128 v[210:213], v155 offset:5120
	ds_read_b128 v[214:217], v155 offset:6144
	ds_read_b128 v[224:227], v155 offset:7168
	global_load_lds_dwordx4 v[148:149], off
	v_lshl_add_u64 v[148:149], s[40:41], 0, v[138:139]
	s_mov_b32 m0, s54
	s_nop 0
	global_load_lds_dwordx4 v[148:149], off
	s_cbranch_vccnz .Llw921bw0
	s_waitcnt vmcnt(8)
.Llw921bw0:
	s_waitcnt lgkmcnt(0)
	s_barrier
	s_setprio 1
	s_waitcnt lgkmcnt(0)
	v_mfma_f32_16x16x32_bf16 v[120:123], v[144:147], v[190:193], v[120:123]
	v_mfma_f32_16x16x32_bf16 v[116:119], v[162:165], v[190:193], v[116:119]
	v_mfma_f32_16x16x32_bf16 v[108:111], v[144:147], v[198:201], v[108:111]
	v_mfma_f32_16x16x32_bf16 v[100:103], v[162:165], v[198:201], v[100:103]
	v_mfma_f32_16x16x32_bf16 v[92:95], v[144:147], v[206:209], v[92:95]
	v_mfma_f32_16x16x32_bf16 v[84:87], v[162:165], v[206:209], v[84:87]
	v_mfma_f32_16x16x32_bf16 v[76:79], v[144:147], v[214:217], v[76:79]
	v_mfma_f32_16x16x32_bf16 v[68:71], v[162:165], v[214:217], v[68:71]
	v_mfma_f32_16x16x32_bf16 v[120:123], v[158:161], v[194:197], v[120:123]
	v_mfma_f32_16x16x32_bf16 v[116:119], v[166:169], v[194:197], v[116:119]
	v_mfma_f32_16x16x32_bf16 v[108:111], v[158:161], v[202:205], v[108:111]
	v_mfma_f32_16x16x32_bf16 v[100:103], v[166:169], v[202:205], v[100:103]
	v_mfma_f32_16x16x32_bf16 v[92:95], v[158:161], v[210:213], v[92:95]
	v_mfma_f32_16x16x32_bf16 v[84:87], v[166:169], v[210:213], v[84:87]
	v_mfma_f32_16x16x32_bf16 v[76:79], v[158:161], v[224:227], v[76:79]
	v_mfma_f32_16x16x32_bf16 v[68:71], v[166:169], v[224:227], v[68:71]
	s_setprio 0
	s_setprio 1
	v_mfma_f32_16x16x32_bf16 v[124:127], v[170:173], v[190:193], v[124:127]
	v_mfma_f32_16x16x32_bf16 v[112:115], v[178:181], v[190:193], v[112:115]
	v_mfma_f32_16x16x32_bf16 v[104:107], v[170:173], v[198:201], v[104:107]
	v_mfma_f32_16x16x32_bf16 v[96:99], v[178:181], v[198:201], v[96:99]
	v_mfma_f32_16x16x32_bf16 v[88:91], v[170:173], v[206:209], v[88:91]
	v_mfma_f32_16x16x32_bf16 v[80:83], v[178:181], v[206:209], v[80:83]
	v_mfma_f32_16x16x32_bf16 v[72:75], v[170:173], v[214:217], v[72:75]
	v_mfma_f32_16x16x32_bf16 v[64:67], v[178:181], v[214:217], v[64:67]
	v_mfma_f32_16x16x32_bf16 v[124:127], v[174:177], v[194:197], v[124:127]
	v_mfma_f32_16x16x32_bf16 v[112:115], v[186:189], v[194:197], v[112:115]
	v_mfma_f32_16x16x32_bf16 v[104:107], v[174:177], v[202:205], v[104:107]
	v_mfma_f32_16x16x32_bf16 v[96:99], v[186:189], v[202:205], v[96:99]
	v_mfma_f32_16x16x32_bf16 v[88:91], v[174:177], v[210:213], v[88:91]
	v_mfma_f32_16x16x32_bf16 v[80:83], v[186:189], v[210:213], v[80:83]
	v_mfma_f32_16x16x32_bf16 v[72:75], v[174:177], v[224:227], v[72:75]
	v_mfma_f32_16x16x32_bf16 v[64:67], v[186:189], v[224:227], v[64:67]
	s_setprio 0
	s_waitcnt vmcnt(8)
	s_barrier
	s_mov_b32 m0, s55
	v_lshl_add_u64 v[148:149], s[64:65], 0, v[132:133]
	v_lshl_add_u64 v[182:183], s[64:65], 0, v[128:129]
	s_add_u32 s64, s64, s16
	ds_read_b128 v[190:193], v155 offset:16384
	ds_read_b128 v[194:197], v155 offset:17408
	ds_read_b128 v[198:201], v155 offset:18432
	ds_read_b128 v[202:205], v155 offset:19456
	ds_read_b128 v[206:209], v155 offset:20480
	ds_read_b128 v[210:213], v155 offset:21504
	ds_read_b128 v[214:217], v155 offset:22528
	ds_read_b128 v[224:227], v155 offset:23552
	global_load_lds_dwordx4 v[148:149], off
	s_mov_b32 m0, s56
	s_addc_u32 s65, s65, s17
	s_add_i32 s66, s51, s31
	global_load_lds_dwordx4 v[182:183], off
	v_lshl_add_u64 v[228:229], s[64:65], 0, v[132:133]
	s_mov_b32 m0, s66
	v_lshl_add_u64 v[230:231], s[64:65], 0, v[128:129]
	global_load_lds_dwordx4 v[228:229], off
	s_add_i32 m0, s66, 0x2000
	v_lshl_add_u64 v[232:233], s[42:43], 0, v[134:135]
	global_load_lds_dwordx4 v[230:231], off
	v_lshl_add_u64 v[234:235], s[42:43], 0, v[130:131]
	s_cbranch_vccnz .Llw921bw1
	s_waitcnt vmcnt(6)
.Llw921bw1:
	s_waitcnt lgkmcnt(0)
	s_barrier
	s_setprio 1
	s_waitcnt lgkmcnt(0)
	v_mfma_f32_16x16x32_bf16 v[60:63], v[144:147], v[190:193], v[60:63]
	v_mfma_f32_16x16x32_bf16 v[52:55], v[162:165], v[190:193], v[52:55]
	v_mfma_f32_16x16x32_bf16 v[44:47], v[144:147], v[198:201], v[44:47]
	v_mfma_f32_16x16x32_bf16 v[36:39], v[162:165], v[198:201], v[36:39]
	v_mfma_f32_16x16x32_bf16 v[28:31], v[144:147], v[206:209], v[28:31]
	v_mfma_f32_16x16x32_bf16 v[20:23], v[162:165], v[206:209], v[20:23]
	v_mfma_f32_16x16x32_bf16 v[12:15], v[144:147], v[214:217], v[12:15]
	v_mfma_f32_16x16x32_bf16 v[4:7], v[162:165], v[214:217], v[4:7]
	v_mfma_f32_16x16x32_bf16 v[60:63], v[158:161], v[194:197], v[60:63]
	v_mfma_f32_16x16x32_bf16 v[52:55], v[166:169], v[194:197], v[52:55]
	v_mfma_f32_16x16x32_bf16 v[44:47], v[158:161], v[202:205], v[44:47]
	v_mfma_f32_16x16x32_bf16 v[36:39], v[166:169], v[202:205], v[36:39]
	v_mfma_f32_16x16x32_bf16 v[28:31], v[158:161], v[210:213], v[28:31]
	v_mfma_f32_16x16x32_bf16 v[20:23], v[166:169], v[210:213], v[20:23]
	v_mfma_f32_16x16x32_bf16 v[12:15], v[158:161], v[224:227], v[12:15]
	v_mfma_f32_16x16x32_bf16 v[4:7], v[166:169], v[224:227], v[4:7]
	s_setprio 0
	s_setprio 1
	v_mfma_f32_16x16x32_bf16 v[56:59], v[170:173], v[190:193], v[56:59]
	v_mfma_f32_16x16x32_bf16 v[48:51], v[178:181], v[190:193], v[48:51]
	v_mfma_f32_16x16x32_bf16 v[40:43], v[170:173], v[198:201], v[40:43]
	v_mfma_f32_16x16x32_bf16 v[32:35], v[178:181], v[198:201], v[32:35]
	v_mfma_f32_16x16x32_bf16 v[24:27], v[170:173], v[206:209], v[24:27]
	v_mfma_f32_16x16x32_bf16 v[16:19], v[178:181], v[206:209], v[16:19]
	v_mfma_f32_16x16x32_bf16 v[8:11], v[170:173], v[214:217], v[8:11]
	v_mfma_f32_16x16x32_bf16 v[0:3], v[178:181], v[214:217], v[0:3]
	v_mfma_f32_16x16x32_bf16 v[56:59], v[174:177], v[194:197], v[56:59]
	v_mfma_f32_16x16x32_bf16 v[48:51], v[186:189], v[194:197], v[48:51]
	v_mfma_f32_16x16x32_bf16 v[40:43], v[174:177], v[202:205], v[40:43]
	v_mfma_f32_16x16x32_bf16 v[32:35], v[186:189], v[202:205], v[32:35]
	v_mfma_f32_16x16x32_bf16 v[24:27], v[174:177], v[210:213], v[24:27]
	v_mfma_f32_16x16x32_bf16 v[16:19], v[186:189], v[210:213], v[16:19]
	v_mfma_f32_16x16x32_bf16 v[8:11], v[174:177], v[224:227], v[8:11]
	v_mfma_f32_16x16x32_bf16 v[0:3], v[186:189], v[224:227], v[0:3]
	s_setprio 0
	s_waitcnt vmcnt(6)
	s_barrier
	s_add_i32 s64, 0, 0x18000
	v_add_u32_e32 v157, s64, v151
	s_add_i32 s65, 0, 0x1c000
	ds_read_b128 v[144:147], v157
	ds_read_b128 v[158:161], v157 offset:1024
	ds_read_b128 v[162:165], v157 offset:2048
	ds_read_b128 v[166:169], v157 offset:3072
	v_add_u32_e32 v157, s65, v151
	ds_read_b128 v[170:173], v157
	ds_read_b128 v[174:177], v157 offset:1024
	ds_read_b128 v[178:181], v157 offset:2048
	ds_read_b128 v[186:189], v157 offset:3072
	s_add_u32 s42, s42, s16
	s_addc_u32 s43, s43, s17
	s_mov_b32 m0, s28
	s_nop 0
	global_load_lds_dwordx4 v[232:233], off
	s_mov_b32 m0, s33
	s_nop 0
	global_load_lds_dwordx4 v[234:235], off
	s_mov_b32 m0, s44
	v_lshl_add_u64 v[236:237], s[42:43], 0, v[134:135]
	ds_read_b128 v[190:193], v155 offset:32768
	ds_read_b128 v[194:197], v155 offset:33792
	ds_read_b128 v[198:201], v155 offset:34816
	ds_read_b128 v[202:205], v155 offset:35840
	ds_read_b128 v[206:209], v155 offset:36864
	ds_read_b128 v[210:213], v155 offset:37888
	ds_read_b128 v[214:217], v155 offset:38912
	ds_read_b128 v[224:227], v155 offset:39936
	global_load_lds_dwordx4 v[236:237], off
	v_lshl_add_u64 v[236:237], s[42:43], 0, v[130:131]
	s_mov_b32 m0, s45
	s_nop 0
	global_load_lds_dwordx4 v[236:237], off
	s_cbranch_vccnz .Llw921bw2
	s_waitcnt vmcnt(8)

.Llw921bw3:
	s_waitcnt lgkmcnt(0)
	s_barrier
	s_setprio 1
	s_waitcnt lgkmcnt(0)
	v_mfma_f32_16x16x32_bf16 v[60:63], v[144:147], v[190:193], v[60:63]
	v_mfma_f32_16x16x32_bf16 v[52:55], v[162:165], v[190:193], v[52:55]
	v_mfma_f32_16x16x32_bf16 v[44:47], v[144:147], v[198:201], v[44:47]
	v_mfma_f32_16x16x32_bf16 v[36:39], v[162:165], v[198:201], v[36:39]
	v_mfma_f32_16x16x32_bf16 v[28:31], v[144:147], v[206:209], v[28:31]
	v_mfma_f32_16x16x32_bf16 v[20:23], v[162:165], v[206:209], v[20:23]
	v_mfma_f32_16x16x32_bf16 v[12:15], v[144:147], v[214:217], v[12:15]
	v_mfma_f32_16x16x32_bf16 v[4:7], v[162:165], v[214:217], v[4:7]
	v_mfma_f32_16x16x32_bf16 v[60:63], v[158:161], v[194:197], v[60:63]
	v_mfma_f32_16x16x32_bf16 v[52:55], v[166:169], v[194:197], v[52:55]
	v_mfma_f32_16x16x32_bf16 v[44:47], v[158:161], v[202:205], v[44:47]
	v_mfma_f32_16x16x32_bf16 v[36:39], v[166:169], v[202:205], v[36:39]
	v_mfma_f32_16x16x32_bf16 v[28:31], v[158:161], v[210:213], v[28:31]
	v_mfma_f32_16x16x32_bf16 v[20:23], v[166:169], v[210:213], v[20:23]
	v_mfma_f32_16x16x32_bf16 v[12:15], v[158:161], v[224:227], v[12:15]
	v_mfma_f32_16x16x32_bf16 v[4:7], v[166:169], v[224:227], v[4:7]
	s_setprio 0
	s_setprio 1
	v_mfma_f32_16x16x32_bf16 v[56:59], v[170:173], v[190:193], v[56:59]
	v_mfma_f32_16x16x32_bf16 v[48:51], v[178:181], v[190:193], v[48:51]
	v_mfma_f32_16x16x32_bf16 v[40:43], v[170:173], v[198:201], v[40:43]
	v_mfma_f32_16x16x32_bf16 v[32:35], v[178:181], v[198:201], v[32:35]
	v_mfma_f32_16x16x32_bf16 v[24:27], v[170:173], v[206:209], v[24:27]
	v_mfma_f32_16x16x32_bf16 v[16:19], v[178:181], v[206:209], v[16:19]
	v_mfma_f32_16x16x32_bf16 v[8:11], v[170:173], v[214:217], v[8:11]
	v_mfma_f32_16x16x32_bf16 v[0:3], v[178:181], v[214:217], v[0:3]
	v_mfma_f32_16x16x32_bf16 v[56:59], v[174:177], v[194:197], v[56:59]
	v_mfma_f32_16x16x32_bf16 v[48:51], v[186:189], v[194:197], v[48:51]
	v_mfma_f32_16x16x32_bf16 v[40:43], v[174:177], v[202:205], v[40:43]
	v_mfma_f32_16x16x32_bf16 v[32:35], v[186:189], v[202:205], v[32:35]
	v_mfma_f32_16x16x32_bf16 v[24:27], v[174:177], v[210:213], v[24:27]
	v_mfma_f32_16x16x32_bf16 v[16:19], v[186:189], v[210:213], v[16:19]
	v_mfma_f32_16x16x32_bf16 v[8:11], v[174:177], v[224:227], v[8:11]
	v_mfma_f32_16x16x32_bf16 v[0:3], v[186:189], v[224:227], v[0:3]
	s_setprio 0
	s_waitcnt vmcnt(6)
	s_barrier
	s_add_u32 s40, s40, 0x100
	s_addc_u32 s41, s41, 0
	s_add_u32 s61, s61, 0x100
	s_addc_u32 s62, s62, 0
	s_cmp_ge_i32 s63, s49
	s_mov_b32 s42, s63
	s_cbranch_scc0 .LBB0_921
	s_branch .LBB0_922

.LBB0_1001:
	s_and_b64 vcc, exec, s[4:5]
	s_waitcnt lgkmcnt(0)
	s_cbranch_vccnz .Lzx1003
	s_add_u32 s44, s44, 0x80
	s_addc_u32 s45, s45, 0
	s_add_u32 s59, s46, 0x100
	s_addc_u32 s60, s47, 0
	s_mov_b32 s46, 0
	s_and_b64 vcc, exec, s[94:95]
	ds_read_b128 v[144:147], v151
	ds_read_b128 v[154:157], v151 offset:1024
	ds_read_b128 v[158:161], v151 offset:2048
	ds_read_b128 v[162:165], v151 offset:3072
	ds_read_b128 v[166:169], v152
	ds_read_b128 v[170:173], v152 offset:1024
	ds_read_b128 v[174:177], v152 offset:2048
	ds_read_b128 v[178:181], v152 offset:3072
	s_add_i32 s61, s46, 2
	s_add_u32 s62, s44, 0x80
	s_addc_u32 s47, s45, 0
	s_cmp_eq_u32 s52, s46
	s_cselect_b32 s46, s8, s62
	s_cselect_b32 s47, s9, s47
	s_cselect_b32 s63, s43, s60
	s_cselect_b32 s62, s42, s59
	v_lshl_add_u64 v[182:183], s[44:45], 0, v[136:137]
	s_add_i32 m0, s3, 0xc000
	ds_read_b128 v[186:189], v153
	ds_read_b128 v[190:193], v153 offset:1024
	ds_read_b128 v[194:197], v153 offset:2048
	ds_read_b128 v[198:201], v153 offset:3072
	ds_read_b128 v[202:205], v153 offset:4096
	ds_read_b128 v[206:209], v153 offset:5120
	ds_read_b128 v[210:213], v153 offset:6144
	ds_read_b128 v[214:217], v153 offset:7168
	global_load_lds_dwordx4 v[182:183], off
	v_lshl_add_u64 v[182:183], s[44:45], 0, v[138:139]
	s_add_i32 m0, s3, 0xe000
	s_nop 0
	global_load_lds_dwordx4 v[182:183], off
	s_cbranch_vccnz .Llw1003pw0
	s_waitcnt vmcnt(8)
.Llw1003pw0:
	s_waitcnt lgkmcnt(0)
	s_barrier
	s_setprio 1
	s_waitcnt lgkmcnt(0)
	v_mfma_f32_16x16x32_bf16 v[124:127], v[144:147], v[186:189], 0
	v_mfma_f32_16x16x32_bf16 v[120:123], v[158:161], v[186:189], 0
	v_mfma_f32_16x16x32_bf16 v[108:111], v[144:147], v[194:197], 0
	v_mfma_f32_16x16x32_bf16 v[104:107], v[158:161], v[194:197], 0
	v_mfma_f32_16x16x32_bf16 v[92:95], v[144:147], v[202:205], 0
	v_mfma_f32_16x16x32_bf16 v[88:91], v[158:161], v[202:205], 0
	v_mfma_f32_16x16x32_bf16 v[76:79], v[144:147], v[210:213], 0
	v_mfma_f32_16x16x32_bf16 v[72:75], v[158:161], v[210:213], 0
	v_mfma_f32_16x16x32_bf16 v[124:127], v[154:157], v[190:193], v[124:127]
	v_mfma_f32_16x16x32_bf16 v[120:123], v[162:165], v[190:193], v[120:123]
	v_mfma_f32_16x16x32_bf16 v[108:111], v[154:157], v[198:201], v[108:111]
	v_mfma_f32_16x16x32_bf16 v[104:107], v[162:165], v[198:201], v[104:107]
	v_mfma_f32_16x16x32_bf16 v[92:95], v[154:157], v[206:209], v[92:95]
	v_mfma_f32_16x16x32_bf16 v[88:91], v[162:165], v[206:209], v[88:91]
	v_mfma_f32_16x16x32_bf16 v[76:79], v[154:157], v[214:217], v[76:79]
	v_mfma_f32_16x16x32_bf16 v[72:75], v[162:165], v[214:217], v[72:75]
	s_setprio 0
	s_setprio 1
	v_mfma_f32_16x16x32_bf16 v[116:119], v[166:169], v[186:189], 0
	v_mfma_f32_16x16x32_bf16 v[112:115], v[174:177], v[186:189], 0
	v_mfma_f32_16x16x32_bf16 v[100:103], v[166:169], v[194:197], 0
	v_mfma_f32_16x16x32_bf16 v[96:99], v[174:177], v[194:197], 0
	v_mfma_f32_16x16x32_bf16 v[84:87], v[166:169], v[202:205], 0
	v_mfma_f32_16x16x32_bf16 v[80:83], v[174:177], v[202:205], 0
	v_mfma_f32_16x16x32_bf16 v[68:71], v[166:169], v[210:213], 0
	v_mfma_f32_16x16x32_bf16 v[64:67], v[174:177], v[210:213], 0
	v_mfma_f32_16x16x32_bf16 v[116:119], v[170:173], v[190:193], v[116:119]
	v_mfma_f32_16x16x32_bf16 v[112:115], v[178:181], v[190:193], v[112:115]
	v_mfma_f32_16x16x32_bf16 v[100:103], v[170:173], v[198:201], v[100:103]
	v_mfma_f32_16x16x32_bf16 v[96:99], v[178:181], v[198:201], v[96:99]
	v_mfma_f32_16x16x32_bf16 v[84:87], v[170:173], v[206:209], v[84:87]
	v_mfma_f32_16x16x32_bf16 v[80:83], v[178:181], v[206:209], v[80:83]
	v_mfma_f32_16x16x32_bf16 v[68:71], v[170:173], v[214:217], v[68:71]
	v_mfma_f32_16x16x32_bf16 v[64:67], v[178:181], v[214:217], v[64:67]
	s_setprio 0
	s_waitcnt vmcnt(8)
	s_barrier
	s_add_i32 s64, s53, s31
	v_lshl_add_u64 v[182:183], s[62:63], 0, v[130:131]
	s_mov_b32 m0, s64
	ds_read_b128 v[186:189], v153 offset:16384
	ds_read_b128 v[190:193], v153 offset:17408
	ds_read_b128 v[194:197], v153 offset:18432
	ds_read_b128 v[198:201], v153 offset:19456
	ds_read_b128 v[202:205], v153 offset:20480
	ds_read_b128 v[206:209], v153 offset:21504
	ds_read_b128 v[210:213], v153 offset:22528
	ds_read_b128 v[214:217], v153 offset:23552
	global_load_lds_dwordx4 v[182:183], off
	s_add_i32 m0, s64, 0x2000
	v_lshl_add_u64 v[224:225], s[62:63], 0, v[134:135]
	s_add_u32 s62, s62, s16
	s_addc_u32 s63, s63, s17
	s_add_i32 s64, s54, s31
	global_load_lds_dwordx4 v[224:225], off
	v_lshl_add_u64 v[226:227], s[62:63], 0, v[130:131]
	s_mov_b32 m0, s64
	v_lshl_add_u64 v[228:229], s[62:63], 0, v[134:135]
	global_load_lds_dwordx4 v[226:227], off
	s_add_i32 m0, s64, 0x2000
	v_lshl_add_u64 v[230:231], s[46:47], 0, v[128:129]
	global_load_lds_dwordx4 v[228:229], off
	v_lshl_add_u64 v[232:233], s[46:47], 0, v[132:133]
	s_cbranch_vccnz .Llw1003pw1
	s_waitcnt vmcnt(6)
.Llw1003pw1:
	s_waitcnt lgkmcnt(0)
	s_barrier
	s_setprio 1
	s_waitcnt lgkmcnt(0)
	v_mfma_f32_16x16x32_bf16 v[60:63], v[144:147], v[186:189], 0
	v_mfma_f32_16x16x32_bf16 v[56:59], v[158:161], v[186:189], 0
	v_mfma_f32_16x16x32_bf16 v[44:47], v[144:147], v[194:197], 0
	v_mfma_f32_16x16x32_bf16 v[40:43], v[158:161], v[194:197], 0
	v_mfma_f32_16x16x32_bf16 v[28:31], v[144:147], v[202:205], 0
	v_mfma_f32_16x16x32_bf16 v[24:27], v[158:161], v[202:205], 0
	v_mfma_f32_16x16x32_bf16 v[12:15], v[144:147], v[210:213], 0
	v_mfma_f32_16x16x32_bf16 v[8:11], v[158:161], v[210:213], 0
	v_mfma_f32_16x16x32_bf16 v[60:63], v[154:157], v[190:193], v[60:63]
	v_mfma_f32_16x16x32_bf16 v[56:59], v[162:165], v[190:193], v[56:59]
	v_mfma_f32_16x16x32_bf16 v[44:47], v[154:157], v[198:201], v[44:47]
	v_mfma_f32_16x16x32_bf16 v[40:43], v[162:165], v[198:201], v[40:43]
	v_mfma_f32_16x16x32_bf16 v[28:31], v[154:157], v[206:209], v[28:31]
	v_mfma_f32_16x16x32_bf16 v[24:27], v[162:165], v[206:209], v[24:27]
	v_mfma_f32_16x16x32_bf16 v[12:15], v[154:157], v[214:217], v[12:15]
	v_mfma_f32_16x16x32_bf16 v[8:11], v[162:165], v[214:217], v[8:11]
	s_setprio 0
	s_setprio 1
	v_mfma_f32_16x16x32_bf16 v[52:55], v[166:169], v[186:189], 0
	v_mfma_f32_16x16x32_bf16 v[48:51], v[174:177], v[186:189], 0
	v_mfma_f32_16x16x32_bf16 v[36:39], v[166:169], v[194:197], 0
	v_mfma_f32_16x16x32_bf16 v[32:35], v[174:177], v[194:197], 0
	v_mfma_f32_16x16x32_bf16 v[20:23], v[166:169], v[202:205], 0
	v_mfma_f32_16x16x32_bf16 v[16:19], v[174:177], v[202:205], 0
	v_mfma_f32_16x16x32_bf16 v[4:7], v[166:169], v[210:213], 0
	v_mfma_f32_16x16x32_bf16 v[0:3], v[174:177], v[210:213], 0
	v_mfma_f32_16x16x32_bf16 v[52:55], v[170:173], v[190:193], v[52:55]
	v_mfma_f32_16x16x32_bf16 v[48:51], v[178:181], v[190:193], v[48:51]
	v_mfma_f32_16x16x32_bf16 v[36:39], v[170:173], v[198:201], v[36:39]
	v_mfma_f32_16x16x32_bf16 v[32:35], v[178:181], v[198:201], v[32:35]
	v_mfma_f32_16x16x32_bf16 v[20:23], v[170:173], v[206:209], v[20:23]
	v_mfma_f32_16x16x32_bf16 v[16:19], v[178:181], v[206:209], v[16:19]
	v_mfma_f32_16x16x32_bf16 v[4:7], v[170:173], v[214:217], v[4:7]
	v_mfma_f32_16x16x32_bf16 v[0:3], v[178:181], v[214:217], v[0:3]
	s_setprio 0
	s_waitcnt vmcnt(6)
	s_barrier
	s_add_i32 s62, 0, 0x18000
	s_add_i32 s63, 0, 0x1c000
	v_add_u32_e32 v162, s62, v149
	v_add_u32_e32 v178, s63, v149
	ds_read_b128 v[144:147], v162
	ds_read_b128 v[154:157], v162 offset:1024
	ds_read_b128 v[158:161], v162 offset:2048
	ds_read_b128 v[162:165], v162 offset:3072
	ds_read_b128 v[166:169], v178
	ds_read_b128 v[170:173], v178 offset:1024
	ds_read_b128 v[174:177], v178 offset:2048
	ds_read_b128 v[178:181], v178 offset:3072
	s_add_u32 s46, s46, s16
	s_addc_u32 s47, s47, s17
	s_mov_b32 m0, s3
	s_nop 0
	global_load_lds_dwordx4 v[230:231], off
	s_mov_b32 m0, s28
	s_nop 0
	global_load_lds_dwordx4 v[232:233], off
	s_mov_b32 m0, s33
	v_lshl_add_u64 v[234:235], s[46:47], 0, v[128:129]
	ds_read_b128 v[186:189], v153 offset:32768
	ds_read_b128 v[190:193], v153 offset:33792
	ds_read_b128 v[194:197], v153 offset:34816
	ds_read_b128 v[198:201], v153 offset:35840
	ds_read_b128 v[202:205], v153 offset:36864
	ds_read_b128 v[206:209], v153 offset:37888
	ds_read_b128 v[210:213], v153 offset:38912
	ds_read_b128 v[214:217], v153 offset:39936
	global_load_lds_dwordx4 v[234:235], off
	v_lshl_add_u64 v[234:235], s[46:47], 0, v[132:133]
	s_mov_b32 m0, s48
	s_nop 0
	global_load_lds_dwordx4 v[234:235], off
	s_cbranch_vccnz .Llw1003pw2
	s_waitcnt vmcnt(8)
.Llw1003pw2:
	s_waitcnt lgkmcnt(0)
	s_barrier
	s_setprio 1
	s_waitcnt lgkmcnt(0)
	v_mfma_f32_16x16x32_bf16 v[124:127], v[144:147], v[186:189], v[124:127]
	v_mfma_f32_16x16x32_bf16 v[120:123], v[158:161], v[186:189], v[120:123]
	v_mfma_f32_16x16x32_bf16 v[108:111], v[144:147], v[194:197], v[108:111]
	v_mfma_f32_16x16x32_bf16 v[104:107], v[158:161], v[194:197], v[104:107]
	v_mfma_f32_16x16x32_bf16 v[92:95], v[144:147], v[202:205], v[92:95]
	v_mfma_f32_16x16x32_bf16 v[88:91], v[158:161], v[202:205], v[88:91]
	v_mfma_f32_16x16x32_bf16 v[76:79], v[144:147], v[210:213], v[76:79]
	v_mfma_f32_16x16x32_bf16 v[72:75], v[158:161], v[210:213], v[72:75]
	v_mfma_f32_16x16x32_bf16 v[124:127], v[154:157], v[190:193], v[124:127]
	v_mfma_f32_16x16x32_bf16 v[120:123], v[162:165], v[190:193], v[120:123]
	v_mfma_f32_16x16x32_bf16 v[108:111], v[154:157], v[198:201], v[108:111]
	v_mfma_f32_16x16x32_bf16 v[104:107], v[162:165], v[198:201], v[104:107]
	v_mfma_f32_16x16x32_bf16 v[92:95], v[154:157], v[206:209], v[92:95]
	v_mfma_f32_16x16x32_bf16 v[88:91], v[162:165], v[206:209], v[88:91]
	v_mfma_f32_16x16x32_bf16 v[76:79], v[154:157], v[214:217], v[76:79]
	v_mfma_f32_16x16x32_bf16 v[72:75], v[162:165], v[214:217], v[72:75]
	s_setprio 0
	s_setprio 1
	v_mfma_f32_16x16x32_bf16 v[116:119], v[166:169], v[186:189], v[116:119]
	v_mfma_f32_16x16x32_bf16 v[112:115], v[174:177], v[186:189], v[112:115]
	v_mfma_f32_16x16x32_bf16 v[100:103], v[166:169], v[194:197], v[100:103]
	v_mfma_f32_16x16x32_bf16 v[96:99], v[174:177], v[194:197], v[96:99]
	v_mfma_f32_16x16x32_bf16 v[84:87], v[166:169], v[202:205], v[84:87]
	v_mfma_f32_16x16x32_bf16 v[80:83], v[174:177], v[202:205], v[80:83]
	v_mfma_f32_16x16x32_bf16 v[68:71], v[166:169], v[210:213], v[68:71]
	v_mfma_f32_16x16x32_bf16 v[64:67], v[174:177], v[210:213], v[64:67]
	v_mfma_f32_16x16x32_bf16 v[116:119], v[170:173], v[190:193], v[116:119]
	v_mfma_f32_16x16x32_bf16 v[112:115], v[178:181], v[190:193], v[112:115]
	v_mfma_f32_16x16x32_bf16 v[100:103], v[170:173], v[198:201], v[100:103]
	v_mfma_f32_16x16x32_bf16 v[96:99], v[178:181], v[198:201], v[96:99]
	v_mfma_f32_16x16x32_bf16 v[84:87], v[170:173], v[206:209], v[84:87]
	v_mfma_f32_16x16x32_bf16 v[80:83], v[178:181], v[206:209], v[80:83]
	v_mfma_f32_16x16x32_bf16 v[68:71], v[170:173], v[214:217], v[68:71]
	v_mfma_f32_16x16x32_bf16 v[64:67], v[178:181], v[214:217], v[64:67]
	s_setprio 0
	s_waitcnt vmcnt(8)
	s_barrier
	s_add_i32 s46, s62, s31
	v_lshl_add_u64 v[182:183], v[182:183], 0, s[40:41]
	s_mov_b32 m0, s46
	ds_read_b128 v[186:189], v153 offset:49152
	ds_read_b128 v[190:193], v153 offset:50176
	ds_read_b128 v[194:197], v153 offset:51200
	ds_read_b128 v[198:201], v153 offset:52224
	ds_read_b128 v[202:205], v153 offset:53248
	ds_read_b128 v[206:209], v153 offset:54272
	ds_read_b128 v[210:213], v153 offset:55296
	ds_read_b128 v[214:217], v153 offset:56320
	global_load_lds_dwordx4 v[182:183], off
	v_lshl_add_u64 v[182:183], v[224:225], 0, s[40:41]
	s_add_i32 m0, s46, 0x2000
	s_add_i32 s46, s63, s31
	global_load_lds_dwordx4 v[182:183], off
	v_lshl_add_u64 v[182:183], v[226:227], 0, s[40:41]
	s_mov_b32 m0, s46
	s_nop 0
	global_load_lds_dwordx4 v[182:183], off
	v_lshl_add_u64 v[182:183], v[228:229], 0, s[40:41]
	s_add_i32 m0, s46, 0x2000
	s_nop 0
	global_load_lds_dwordx4 v[182:183], off
	s_cbranch_vccnz .Llw1003pw3
	s_waitcnt vmcnt(6)
.Llw1003pw3:
	s_waitcnt lgkmcnt(0)
	s_barrier
	s_setprio 1
	s_waitcnt lgkmcnt(0)
	v_mfma_f32_16x16x32_bf16 v[60:63], v[144:147], v[186:189], v[60:63]
	v_mfma_f32_16x16x32_bf16 v[56:59], v[158:161], v[186:189], v[56:59]
	v_mfma_f32_16x16x32_bf16 v[44:47], v[144:147], v[194:197], v[44:47]
	v_mfma_f32_16x16x32_bf16 v[40:43], v[158:161], v[194:197], v[40:43]
	v_mfma_f32_16x16x32_bf16 v[28:31], v[144:147], v[202:205], v[28:31]
	v_mfma_f32_16x16x32_bf16 v[24:27], v[158:161], v[202:205], v[24:27]
	v_mfma_f32_16x16x32_bf16 v[12:15], v[144:147], v[210:213], v[12:15]
	v_mfma_f32_16x16x32_bf16 v[8:11], v[158:161], v[210:213], v[8:11]
	v_mfma_f32_16x16x32_bf16 v[60:63], v[154:157], v[190:193], v[60:63]
	v_mfma_f32_16x16x32_bf16 v[56:59], v[162:165], v[190:193], v[56:59]
	v_mfma_f32_16x16x32_bf16 v[44:47], v[154:157], v[198:201], v[44:47]
	v_mfma_f32_16x16x32_bf16 v[40:43], v[162:165], v[198:201], v[40:43]
	v_mfma_f32_16x16x32_bf16 v[28:31], v[154:157], v[206:209], v[28:31]
	v_mfma_f32_16x16x32_bf16 v[24:27], v[162:165], v[206:209], v[24:27]
	v_mfma_f32_16x16x32_bf16 v[12:15], v[154:157], v[214:217], v[12:15]
	v_mfma_f32_16x16x32_bf16 v[8:11], v[162:165], v[214:217], v[8:11]
	s_setprio 0
	s_setprio 1
	v_mfma_f32_16x16x32_bf16 v[52:55], v[166:169], v[186:189], v[52:55]
	v_mfma_f32_16x16x32_bf16 v[48:51], v[174:177], v[186:189], v[48:51]
	v_mfma_f32_16x16x32_bf16 v[36:39], v[166:169], v[194:197], v[36:39]
	v_mfma_f32_16x16x32_bf16 v[32:35], v[174:177], v[194:197], v[32:35]
	v_mfma_f32_16x16x32_bf16 v[20:23], v[166:169], v[202:205], v[20:23]
	v_mfma_f32_16x16x32_bf16 v[16:19], v[174:177], v[202:205], v[16:19]
	v_mfma_f32_16x16x32_bf16 v[4:7], v[166:169], v[210:213], v[4:7]
	v_mfma_f32_16x16x32_bf16 v[0:3], v[174:177], v[210:213], v[0:3]
	v_mfma_f32_16x16x32_bf16 v[52:55], v[170:173], v[190:193], v[52:55]
	v_mfma_f32_16x16x32_bf16 v[48:51], v[178:181], v[190:193], v[48:51]
	v_mfma_f32_16x16x32_bf16 v[36:39], v[170:173], v[198:201], v[36:39]
	v_mfma_f32_16x16x32_bf16 v[32:35], v[178:181], v[198:201], v[32:35]
	v_mfma_f32_16x16x32_bf16 v[20:23], v[170:173], v[206:209], v[20:23]
	v_mfma_f32_16x16x32_bf16 v[16:19], v[178:181], v[206:209], v[16:19]
	v_mfma_f32_16x16x32_bf16 v[4:7], v[170:173], v[214:217], v[4:7]
	v_mfma_f32_16x16x32_bf16 v[0:3], v[178:181], v[214:217], v[0:3]
	s_setprio 0
	s_waitcnt vmcnt(6)
	s_barrier
	s_add_u32 s44, s44, 0x100
	s_addc_u32 s45, s45, 0
	s_add_u32 s59, s59, 0x100
	s_addc_u32 s60, s60, 0
	s_cmp_ge_i32 s61, s51
	s_mov_b32 s46, s61
	s_cbranch_scc1 .LBB0_1004
.LBB0_1003:
	ds_read_b128 v[144:147], v151
	ds_read_b128 v[154:157], v151 offset:1024
	ds_read_b128 v[158:161], v151 offset:2048
	ds_read_b128 v[162:165], v151 offset:3072
	ds_read_b128 v[166:169], v152
	ds_read_b128 v[170:173], v152 offset:1024
	ds_read_b128 v[174:177], v152 offset:2048
	ds_read_b128 v[178:181], v152 offset:3072
	s_add_i32 s61, s46, 2
	s_add_u32 s62, s44, 0x80
	s_addc_u32 s47, s45, 0
	s_cmp_eq_u32 s52, s46
	s_cselect_b32 s46, s8, s62
	s_cselect_b32 s47, s9, s47
	s_cselect_b32 s63, s43, s60
	s_cselect_b32 s62, s42, s59
	v_lshl_add_u64 v[182:183], v[230:231], 0, s[40:41]
	s_mov_b32 m0, s49
	s_nop 0
	global_load_lds_dwordx4 v[182:183], off
	v_lshl_add_u64 v[182:183], v[232:233], 0, s[40:41]
	s_mov_b32 m0, s50
	s_nop 0
	global_load_lds_dwordx4 v[182:183], off
	v_lshl_add_u64 v[182:183], s[44:45], 0, v[136:137]
	s_add_i32 m0, s3, 0xc000
	ds_read_b128 v[186:189], v153
	ds_read_b128 v[190:193], v153 offset:1024
	ds_read_b128 v[194:197], v153 offset:2048
	ds_read_b128 v[198:201], v153 offset:3072
	ds_read_b128 v[202:205], v153 offset:4096
	ds_read_b128 v[206:209], v153 offset:5120
	ds_read_b128 v[210:213], v153 offset:6144
	ds_read_b128 v[214:217], v153 offset:7168
	global_load_lds_dwordx4 v[182:183], off
	v_lshl_add_u64 v[182:183], s[44:45], 0, v[138:139]
	s_add_i32 m0, s3, 0xe000
	s_nop 0
	global_load_lds_dwordx4 v[182:183], off
	s_cbranch_vccnz .Llw1003bw0
	s_waitcnt vmcnt(8)
.Llw1003bw0:
	s_waitcnt lgkmcnt(0)
	s_barrier
	s_setprio 1
	s_waitcnt lgkmcnt(0)
	v_mfma_f32_16x16x32_bf16 v[124:127], v[144:147], v[186:189], v[124:127]
	v_mfma_f32_16x16x32_bf16 v[120:123], v[158:161], v[186:189], v[120:123]
	v_mfma_f32_16x16x32_bf16 v[108:111], v[144:147], v[194:197], v[108:111]
	v_mfma_f32_16x16x32_bf16 v[104:107], v[158:161], v[194:197], v[104:107]
	v_mfma_f32_16x16x32_bf16 v[92:95], v[144:147], v[202:205], v[92:95]
	v_mfma_f32_16x16x32_bf16 v[88:91], v[158:161], v[202:205], v[88:91]
	v_mfma_f32_16x16x32_bf16 v[76:79], v[144:147], v[210:213], v[76:79]
	v_mfma_f32_16x16x32_bf16 v[72:75], v[158:161], v[210:213], v[72:75]
	v_mfma_f32_16x16x32_bf16 v[124:127], v[154:157], v[190:193], v[124:127]
	v_mfma_f32_16x16x32_bf16 v[120:123], v[162:165], v[190:193], v[120:123]
	v_mfma_f32_16x16x32_bf16 v[108:111], v[154:157], v[198:201], v[108:111]
	v_mfma_f32_16x16x32_bf16 v[104:107], v[162:165], v[198:201], v[104:107]
	v_mfma_f32_16x16x32_bf16 v[92:95], v[154:157], v[206:209], v[92:95]
	v_mfma_f32_16x16x32_bf16 v[88:91], v[162:165], v[206:209], v[88:91]
	v_mfma_f32_16x16x32_bf16 v[76:79], v[154:157], v[214:217], v[76:79]
	v_mfma_f32_16x16x32_bf16 v[72:75], v[162:165], v[214:217], v[72:75]
	s_setprio 0
	s_setprio 1
	v_mfma_f32_16x16x32_bf16 v[116:119], v[166:169], v[186:189], v[116:119]
	v_mfma_f32_16x16x32_bf16 v[112:115], v[174:177], v[186:189], v[112:115]
	v_mfma_f32_16x16x32_bf16 v[100:103], v[166:169], v[194:197], v[100:103]
	v_mfma_f32_16x16x32_bf16 v[96:99], v[174:177], v[194:197], v[96:99]
	v_mfma_f32_16x16x32_bf16 v[84:87], v[166:169], v[202:205], v[84:87]
	v_mfma_f32_16x16x32_bf16 v[80:83], v[174:177], v[202:205], v[80:83]
	v_mfma_f32_16x16x32_bf16 v[68:71], v[166:169], v[210:213], v[68:71]
	v_mfma_f32_16x16x32_bf16 v[64:67], v[174:177], v[210:213], v[64:67]
	v_mfma_f32_16x16x32_bf16 v[116:119], v[170:173], v[190:193], v[116:119]
	v_mfma_f32_16x16x32_bf16 v[112:115], v[178:181], v[190:193], v[112:115]
	v_mfma_f32_16x16x32_bf16 v[100:103], v[170:173], v[198:201], v[100:103]
	v_mfma_f32_16x16x32_bf16 v[96:99], v[178:181], v[198:201], v[96:99]
	v_mfma_f32_16x16x32_bf16 v[84:87], v[170:173], v[206:209], v[84:87]
	v_mfma_f32_16x16x32_bf16 v[80:83], v[178:181], v[206:209], v[80:83]
	v_mfma_f32_16x16x32_bf16 v[68:71], v[170:173], v[214:217], v[68:71]
	v_mfma_f32_16x16x32_bf16 v[64:67], v[178:181], v[214:217], v[64:67]
	s_setprio 0
	s_waitcnt vmcnt(8)
	s_barrier
	s_add_i32 s64, s53, s31
	v_lshl_add_u64 v[182:183], s[62:63], 0, v[130:131]
	s_mov_b32 m0, s64
	ds_read_b128 v[186:189], v153 offset:16384
	ds_read_b128 v[190:193], v153 offset:17408
	ds_read_b128 v[194:197], v153 offset:18432
	ds_read_b128 v[198:201], v153 offset:19456
	ds_read_b128 v[202:205], v153 offset:20480
	ds_read_b128 v[206:209], v153 offset:21504
	ds_read_b128 v[210:213], v153 offset:22528
	ds_read_b128 v[214:217], v153 offset:23552
	global_load_lds_dwordx4 v[182:183], off
	s_add_i32 m0, s64, 0x2000
	v_lshl_add_u64 v[224:225], s[62:63], 0, v[134:135]
	s_add_u32 s62, s62, s16
	s_addc_u32 s63, s63, s17
	s_add_i32 s64, s54, s31
	global_load_lds_dwordx4 v[224:225], off
	v_lshl_add_u64 v[226:227], s[62:63], 0, v[130:131]
	s_mov_b32 m0, s64
	v_lshl_add_u64 v[228:229], s[62:63], 0, v[134:135]
	global_load_lds_dwordx4 v[226:227], off
	s_add_i32 m0, s64, 0x2000
	v_lshl_add_u64 v[230:231], s[46:47], 0, v[128:129]
	global_load_lds_dwordx4 v[228:229], off
	v_lshl_add_u64 v[232:233], s[46:47], 0, v[132:133]
	s_cbranch_vccnz .Llw1003bw1
	s_waitcnt vmcnt(6)
.Llw1003bw1:
	s_waitcnt lgkmcnt(0)
	s_barrier
	s_setprio 1
	s_waitcnt lgkmcnt(0)
	v_mfma_f32_16x16x32_bf16 v[60:63], v[144:147], v[186:189], v[60:63]
	v_mfma_f32_16x16x32_bf16 v[56:59], v[158:161], v[186:189], v[56:59]
	v_mfma_f32_16x16x32_bf16 v[44:47], v[144:147], v[194:197], v[44:47]
	v_mfma_f32_16x16x32_bf16 v[40:43], v[158:161], v[194:197], v[40:43]
	v_mfma_f32_16x16x32_bf16 v[28:31], v[144:147], v[202:205], v[28:31]
	v_mfma_f32_16x16x32_bf16 v[24:27], v[158:161], v[202:205], v[24:27]
	v_mfma_f32_16x16x32_bf16 v[12:15], v[144:147], v[210:213], v[12:15]
	v_mfma_f32_16x16x32_bf16 v[8:11], v[158:161], v[210:213], v[8:11]
	v_mfma_f32_16x16x32_bf16 v[60:63], v[154:157], v[190:193], v[60:63]
	v_mfma_f32_16x16x32_bf16 v[56:59], v[162:165], v[190:193], v[56:59]
	v_mfma_f32_16x16x32_bf16 v[44:47], v[154:157], v[198:201], v[44:47]
	v_mfma_f32_16x16x32_bf16 v[40:43], v[162:165], v[198:201], v[40:43]
	v_mfma_f32_16x16x32_bf16 v[28:31], v[154:157], v[206:209], v[28:31]
	v_mfma_f32_16x16x32_bf16 v[24:27], v[162:165], v[206:209], v[24:27]
	v_mfma_f32_16x16x32_bf16 v[12:15], v[154:157], v[214:217], v[12:15]
	v_mfma_f32_16x16x32_bf16 v[8:11], v[162:165], v[214:217], v[8:11]
	s_setprio 0
	s_setprio 1
	v_mfma_f32_16x16x32_bf16 v[52:55], v[166:169], v[186:189], v[52:55]
	v_mfma_f32_16x16x32_bf16 v[48:51], v[174:177], v[186:189], v[48:51]
	v_mfma_f32_16x16x32_bf16 v[36:39], v[166:169], v[194:197], v[36:39]
	v_mfma_f32_16x16x32_bf16 v[32:35], v[174:177], v[194:197], v[32:35]
	v_mfma_f32_16x16x32_bf16 v[20:23], v[166:169], v[202:205], v[20:23]
	v_mfma_f32_16x16x32_bf16 v[16:19], v[174:177], v[202:205], v[16:19]
	v_mfma_f32_16x16x32_bf16 v[4:7], v[166:169], v[210:213], v[4:7]
	v_mfma_f32_16x16x32_bf16 v[0:3], v[174:177], v[210:213], v[0:3]
	v_mfma_f32_16x16x32_bf16 v[52:55], v[170:173], v[190:193], v[52:55]
	v_mfma_f32_16x16x32_bf16 v[48:51], v[178:181], v[190:193], v[48:51]
	v_mfma_f32_16x16x32_bf16 v[36:39], v[170:173], v[198:201], v[36:39]
	v_mfma_f32_16x16x32_bf16 v[32:35], v[178:181], v[198:201], v[32:35]
	v_mfma_f32_16x16x32_bf16 v[20:23], v[170:173], v[206:209], v[20:23]
	v_mfma_f32_16x16x32_bf16 v[16:19], v[178:181], v[206:209], v[16:19]
	v_mfma_f32_16x16x32_bf16 v[4:7], v[170:173], v[214:217], v[4:7]
	v_mfma_f32_16x16x32_bf16 v[0:3], v[178:181], v[214:217], v[0:3]
	s_setprio 0
	s_waitcnt vmcnt(6)
	s_barrier
	s_add_i32 s62, 0, 0x18000
	s_add_i32 s63, 0, 0x1c000
	v_add_u32_e32 v162, s62, v149
	v_add_u32_e32 v178, s63, v149
	ds_read_b128 v[144:147], v162
	ds_read_b128 v[154:157], v162 offset:1024
	ds_read_b128 v[158:161], v162 offset:2048
	ds_read_b128 v[162:165], v162 offset:3072
	ds_read_b128 v[166:169], v178
	ds_read_b128 v[170:173], v178 offset:1024
	ds_read_b128 v[174:177], v178 offset:2048
	ds_read_b128 v[178:181], v178 offset:3072
	s_add_u32 s46, s46, s16
	s_addc_u32 s47, s47, s17
	s_mov_b32 m0, s3
	s_nop 0
	global_load_lds_dwordx4 v[230:231], off
	s_mov_b32 m0, s28
	s_nop 0
	global_load_lds_dwordx4 v[232:233], off
	s_mov_b32 m0, s33
	v_lshl_add_u64 v[234:235], s[46:47], 0, v[128:129]
	ds_read_b128 v[186:189], v153 offset:32768
	ds_read_b128 v[190:193], v153 offset:33792
	ds_read_b128 v[194:197], v153 offset:34816
	ds_read_b128 v[198:201], v153 offset:35840
	ds_read_b128 v[202:205], v153 offset:36864
	ds_read_b128 v[206:209], v153 offset:37888
	ds_read_b128 v[210:213], v153 offset:38912
	ds_read_b128 v[214:217], v153 offset:39936
	global_load_lds_dwordx4 v[234:235], off
	v_lshl_add_u64 v[234:235], s[46:47], 0, v[132:133]
	s_mov_b32 m0, s48
	s_nop 0
	global_load_lds_dwordx4 v[234:235], off
	s_cbranch_vccnz .Llw1003bw2
	s_waitcnt vmcnt(8)

.Llw1003bw3:
	s_waitcnt lgkmcnt(0)
	s_barrier
	s_setprio 1
	s_waitcnt lgkmcnt(0)
	v_mfma_f32_16x16x32_bf16 v[60:63], v[144:147], v[186:189], v[60:63]
	v_mfma_f32_16x16x32_bf16 v[56:59], v[158:161], v[186:189], v[56:59]
	v_mfma_f32_16x16x32_bf16 v[44:47], v[144:147], v[194:197], v[44:47]
	v_mfma_f32_16x16x32_bf16 v[40:43], v[158:161], v[194:197], v[40:43]
	v_mfma_f32_16x16x32_bf16 v[28:31], v[144:147], v[202:205], v[28:31]
	v_mfma_f32_16x16x32_bf16 v[24:27], v[158:161], v[202:205], v[24:27]
	v_mfma_f32_16x16x32_bf16 v[12:15], v[144:147], v[210:213], v[12:15]
	v_mfma_f32_16x16x32_bf16 v[8:11], v[158:161], v[210:213], v[8:11]
	v_mfma_f32_16x16x32_bf16 v[60:63], v[154:157], v[190:193], v[60:63]
	v_mfma_f32_16x16x32_bf16 v[56:59], v[162:165], v[190:193], v[56:59]
	v_mfma_f32_16x16x32_bf16 v[44:47], v[154:157], v[198:201], v[44:47]
	v_mfma_f32_16x16x32_bf16 v[40:43], v[162:165], v[198:201], v[40:43]
	v_mfma_f32_16x16x32_bf16 v[28:31], v[154:157], v[206:209], v[28:31]
	v_mfma_f32_16x16x32_bf16 v[24:27], v[162:165], v[206:209], v[24:27]
	v_mfma_f32_16x16x32_bf16 v[12:15], v[154:157], v[214:217], v[12:15]
	v_mfma_f32_16x16x32_bf16 v[8:11], v[162:165], v[214:217], v[8:11]
	s_setprio 0
	s_setprio 1
	v_mfma_f32_16x16x32_bf16 v[52:55], v[166:169], v[186:189], v[52:55]
	v_mfma_f32_16x16x32_bf16 v[48:51], v[174:177], v[186:189], v[48:51]
	v_mfma_f32_16x16x32_bf16 v[36:39], v[166:169], v[194:197], v[36:39]
	v_mfma_f32_16x16x32_bf16 v[32:35], v[174:177], v[194:197], v[32:35]
	v_mfma_f32_16x16x32_bf16 v[20:23], v[166:169], v[202:205], v[20:23]
	v_mfma_f32_16x16x32_bf16 v[16:19], v[174:177], v[202:205], v[16:19]
	v_mfma_f32_16x16x32_bf16 v[4:7], v[166:169], v[210:213], v[4:7]
	v_mfma_f32_16x16x32_bf16 v[0:3], v[174:177], v[210:213], v[0:3]
	v_mfma_f32_16x16x32_bf16 v[52:55], v[170:173], v[190:193], v[52:55]
	v_mfma_f32_16x16x32_bf16 v[48:51], v[178:181], v[190:193], v[48:51]
	v_mfma_f32_16x16x32_bf16 v[36:39], v[170:173], v[198:201], v[36:39]
	v_mfma_f32_16x16x32_bf16 v[32:35], v[178:181], v[198:201], v[32:35]
	v_mfma_f32_16x16x32_bf16 v[20:23], v[170:173], v[206:209], v[20:23]
	v_mfma_f32_16x16x32_bf16 v[16:19], v[178:181], v[206:209], v[16:19]
	v_mfma_f32_16x16x32_bf16 v[4:7], v[170:173], v[214:217], v[4:7]
	v_mfma_f32_16x16x32_bf16 v[0:3], v[178:181], v[214:217], v[0:3]
	s_setprio 0
	s_waitcnt vmcnt(6)
	s_barrier
	s_add_u32 s44, s44, 0x100
	s_addc_u32 s45, s45, 0
	s_add_u32 s59, s59, 0x100
	s_addc_u32 s60, s60, 0
	s_cmp_ge_i32 s61, s51
	s_mov_b32 s46, s61
	s_cbranch_scc0 .LBB0_1003
	s_branch .LBB0_1004

.LBB0_1110:
	s_andn2_b64 vcc, exec, s[38:39]
	s_cbranch_vccnz .Lzx1112
	s_add_u32 s4, s48, 0x80
	s_addc_u32 s5, s49, 0
	s_add_u32 s33, s46, 0x100
	s_addc_u32 s48, s47, 0
	s_mov_b32 s46, 0
	s_and_b64 vcc, exec, s[94:95]
	ds_read_b128 v[144:147], v151
	ds_read_b128 v[156:159], v151 offset:1024
	ds_read_b128 v[160:163], v151 offset:2048
	ds_read_b128 v[164:167], v151 offset:3072
	ds_read_b128 v[168:171], v152
	ds_read_b128 v[172:175], v152 offset:1024
	ds_read_b128 v[176:179], v152 offset:2048
	ds_read_b128 v[180:183], v152 offset:3072
	s_add_i32 s49, s46, 2
	s_add_u32 s52, s4, 0x80
	s_addc_u32 s47, s5, 0
	s_cmp_eq_u32 s60, s46
	s_cselect_b32 s46, s42, s52
	s_cselect_b32 s47, s43, s47
	s_cselect_b32 s53, s45, s48
	s_cselect_b32 s52, s44, s33
	v_lshl_add_u64 v[224:225], s[4:5], 0, v[136:137]
	s_add_i32 m0, s50, 0xc000
	ds_read_b128 v[186:189], v153
	ds_read_b128 v[190:193], v153 offset:1024
	ds_read_b128 v[194:197], v153 offset:2048
	ds_read_b128 v[198:201], v153 offset:3072
	ds_read_b128 v[202:205], v153 offset:4096
	ds_read_b128 v[206:209], v153 offset:5120
	ds_read_b128 v[210:213], v153 offset:6144
	ds_read_b128 v[214:217], v153 offset:7168
	global_load_lds_dwordx4 v[224:225], off
	v_lshl_add_u64 v[224:225], s[4:5], 0, v[138:139]
	s_add_i32 m0, s50, 0xe000
	s_nop 0
	global_load_lds_dwordx4 v[224:225], off
	s_cbranch_vccnz .Llw1112pw0
	s_waitcnt vmcnt(8)
.Llw1112pw0:
	s_waitcnt lgkmcnt(0)
	s_barrier
	s_setprio 1
	s_waitcnt lgkmcnt(0)
	v_mfma_f32_16x16x32_bf16 v[124:127], v[144:147], v[186:189], 0
	v_mfma_f32_16x16x32_bf16 v[120:123], v[160:163], v[186:189], 0
	v_mfma_f32_16x16x32_bf16 v[108:111], v[144:147], v[194:197], 0
	v_mfma_f32_16x16x32_bf16 v[104:107], v[160:163], v[194:197], 0
	v_mfma_f32_16x16x32_bf16 v[92:95], v[144:147], v[202:205], 0
	v_mfma_f32_16x16x32_bf16 v[88:91], v[160:163], v[202:205], 0
	v_mfma_f32_16x16x32_bf16 v[76:79], v[144:147], v[210:213], 0
	v_mfma_f32_16x16x32_bf16 v[72:75], v[160:163], v[210:213], 0
	v_mfma_f32_16x16x32_bf16 v[124:127], v[156:159], v[190:193], v[124:127]
	v_mfma_f32_16x16x32_bf16 v[120:123], v[164:167], v[190:193], v[120:123]
	v_mfma_f32_16x16x32_bf16 v[108:111], v[156:159], v[198:201], v[108:111]
	v_mfma_f32_16x16x32_bf16 v[104:107], v[164:167], v[198:201], v[104:107]
	v_mfma_f32_16x16x32_bf16 v[92:95], v[156:159], v[206:209], v[92:95]
	v_mfma_f32_16x16x32_bf16 v[88:91], v[164:167], v[206:209], v[88:91]
	v_mfma_f32_16x16x32_bf16 v[76:79], v[156:159], v[214:217], v[76:79]
	v_mfma_f32_16x16x32_bf16 v[72:75], v[164:167], v[214:217], v[72:75]
	s_setprio 0
	s_setprio 1
	v_mfma_f32_16x16x32_bf16 v[116:119], v[168:171], v[186:189], 0
	v_mfma_f32_16x16x32_bf16 v[112:115], v[176:179], v[186:189], 0
	v_mfma_f32_16x16x32_bf16 v[100:103], v[168:171], v[194:197], 0
	v_mfma_f32_16x16x32_bf16 v[96:99], v[176:179], v[194:197], 0
	v_mfma_f32_16x16x32_bf16 v[84:87], v[168:171], v[202:205], 0
	v_mfma_f32_16x16x32_bf16 v[80:83], v[176:179], v[202:205], 0
	v_mfma_f32_16x16x32_bf16 v[68:71], v[168:171], v[210:213], 0
	v_mfma_f32_16x16x32_bf16 v[64:67], v[176:179], v[210:213], 0
	v_mfma_f32_16x16x32_bf16 v[116:119], v[172:175], v[190:193], v[116:119]
	v_mfma_f32_16x16x32_bf16 v[112:115], v[180:183], v[190:193], v[112:115]
	v_mfma_f32_16x16x32_bf16 v[100:103], v[172:175], v[198:201], v[100:103]
	v_mfma_f32_16x16x32_bf16 v[96:99], v[180:183], v[198:201], v[96:99]
	v_mfma_f32_16x16x32_bf16 v[84:87], v[172:175], v[206:209], v[84:87]
	v_mfma_f32_16x16x32_bf16 v[80:83], v[180:183], v[206:209], v[80:83]
	v_mfma_f32_16x16x32_bf16 v[68:71], v[172:175], v[214:217], v[68:71]
	v_mfma_f32_16x16x32_bf16 v[64:67], v[180:183], v[214:217], v[64:67]
	s_setprio 0
	s_waitcnt vmcnt(8)
	s_barrier
	s_add_i32 s65, s61, s31
	v_lshl_add_u64 v[224:225], s[52:53], 0, v[130:131]
	s_mov_b32 m0, s65
	ds_read_b128 v[186:189], v153 offset:16384
	ds_read_b128 v[190:193], v153 offset:17408
	ds_read_b128 v[194:197], v153 offset:18432
	ds_read_b128 v[198:201], v153 offset:19456
	ds_read_b128 v[202:205], v153 offset:20480
	ds_read_b128 v[206:209], v153 offset:21504
	ds_read_b128 v[210:213], v153 offset:22528
	ds_read_b128 v[214:217], v153 offset:23552
	global_load_lds_dwordx4 v[224:225], off
	s_add_i32 m0, s65, 0x2000
	v_lshl_add_u64 v[226:227], s[52:53], 0, v[134:135]
	s_add_u32 s52, s52, s14
	s_addc_u32 s53, s53, s15
	s_add_i32 s65, s62, s31
	global_load_lds_dwordx4 v[226:227], off
	v_lshl_add_u64 v[228:229], s[52:53], 0, v[130:131]
	s_mov_b32 m0, s65
	v_lshl_add_u64 v[230:231], s[52:53], 0, v[134:135]
	global_load_lds_dwordx4 v[228:229], off
	s_add_i32 m0, s65, 0x2000
	v_lshl_add_u64 v[232:233], s[46:47], 0, v[128:129]
	global_load_lds_dwordx4 v[230:231], off
	v_lshl_add_u64 v[234:235], s[46:47], 0, v[132:133]
	s_cbranch_vccnz .Llw1112pw1
	s_waitcnt vmcnt(6)
.Llw1112pw1:
	s_waitcnt lgkmcnt(0)
	s_barrier
	s_setprio 1
	s_waitcnt lgkmcnt(0)
	v_mfma_f32_16x16x32_bf16 v[60:63], v[144:147], v[186:189], 0
	v_mfma_f32_16x16x32_bf16 v[56:59], v[160:163], v[186:189], 0
	v_mfma_f32_16x16x32_bf16 v[44:47], v[144:147], v[194:197], 0
	v_mfma_f32_16x16x32_bf16 v[40:43], v[160:163], v[194:197], 0
	v_mfma_f32_16x16x32_bf16 v[28:31], v[144:147], v[202:205], 0
	v_mfma_f32_16x16x32_bf16 v[24:27], v[160:163], v[202:205], 0
	v_mfma_f32_16x16x32_bf16 v[12:15], v[144:147], v[210:213], 0
	v_mfma_f32_16x16x32_bf16 v[8:11], v[160:163], v[210:213], 0
	v_mfma_f32_16x16x32_bf16 v[60:63], v[156:159], v[190:193], v[60:63]
	v_mfma_f32_16x16x32_bf16 v[56:59], v[164:167], v[190:193], v[56:59]
	v_mfma_f32_16x16x32_bf16 v[44:47], v[156:159], v[198:201], v[44:47]
	v_mfma_f32_16x16x32_bf16 v[40:43], v[164:167], v[198:201], v[40:43]
	v_mfma_f32_16x16x32_bf16 v[28:31], v[156:159], v[206:209], v[28:31]
	v_mfma_f32_16x16x32_bf16 v[24:27], v[164:167], v[206:209], v[24:27]
	v_mfma_f32_16x16x32_bf16 v[12:15], v[156:159], v[214:217], v[12:15]
	v_mfma_f32_16x16x32_bf16 v[8:11], v[164:167], v[214:217], v[8:11]
	s_setprio 0
	s_setprio 1
	v_mfma_f32_16x16x32_bf16 v[52:55], v[168:171], v[186:189], 0
	v_mfma_f32_16x16x32_bf16 v[48:51], v[176:179], v[186:189], 0
	v_mfma_f32_16x16x32_bf16 v[36:39], v[168:171], v[194:197], 0
	v_mfma_f32_16x16x32_bf16 v[32:35], v[176:179], v[194:197], 0
	v_mfma_f32_16x16x32_bf16 v[20:23], v[168:171], v[202:205], 0
	v_mfma_f32_16x16x32_bf16 v[16:19], v[176:179], v[202:205], 0
	v_mfma_f32_16x16x32_bf16 v[4:7], v[168:171], v[210:213], 0
	v_mfma_f32_16x16x32_bf16 v[0:3], v[176:179], v[210:213], 0
	v_mfma_f32_16x16x32_bf16 v[52:55], v[172:175], v[190:193], v[52:55]
	v_mfma_f32_16x16x32_bf16 v[48:51], v[180:183], v[190:193], v[48:51]
	v_mfma_f32_16x16x32_bf16 v[36:39], v[172:175], v[198:201], v[36:39]
	v_mfma_f32_16x16x32_bf16 v[32:35], v[180:183], v[198:201], v[32:35]
	v_mfma_f32_16x16x32_bf16 v[20:23], v[172:175], v[206:209], v[20:23]
	v_mfma_f32_16x16x32_bf16 v[16:19], v[180:183], v[206:209], v[16:19]
	v_mfma_f32_16x16x32_bf16 v[4:7], v[172:175], v[214:217], v[4:7]
	v_mfma_f32_16x16x32_bf16 v[0:3], v[180:183], v[214:217], v[0:3]
	s_setprio 0
	s_waitcnt vmcnt(6)
	s_barrier
	s_add_i32 s52, 0, 0x18000
	v_add_u32_e32 v155, s52, v149
	s_add_i32 s53, 0, 0x1c000
	ds_read_b128 v[144:147], v155
	ds_read_b128 v[156:159], v155 offset:1024
	ds_read_b128 v[160:163], v155 offset:2048
	ds_read_b128 v[164:167], v155 offset:3072
	v_add_u32_e32 v155, s53, v149
	ds_read_b128 v[168:171], v155
	ds_read_b128 v[172:175], v155 offset:1024
	ds_read_b128 v[176:179], v155 offset:2048
	ds_read_b128 v[180:183], v155 offset:3072
	s_add_u32 s46, s46, s14
	s_addc_u32 s47, s47, s15
	s_mov_b32 m0, s50
	s_nop 0
	global_load_lds_dwordx4 v[232:233], off
	s_mov_b32 m0, s51
	s_nop 0
	global_load_lds_dwordx4 v[234:235], off
	s_mov_b32 m0, s54
	v_lshl_add_u64 v[236:237], s[46:47], 0, v[128:129]
	ds_read_b128 v[186:189], v153 offset:32768
	ds_read_b128 v[190:193], v153 offset:33792
	ds_read_b128 v[194:197], v153 offset:34816
	ds_read_b128 v[198:201], v153 offset:35840
	ds_read_b128 v[202:205], v153 offset:36864
	ds_read_b128 v[206:209], v153 offset:37888
	ds_read_b128 v[210:213], v153 offset:38912
	ds_read_b128 v[214:217], v153 offset:39936
	global_load_lds_dwordx4 v[236:237], off
	v_lshl_add_u64 v[236:237], s[46:47], 0, v[132:133]
	s_mov_b32 m0, s55
	s_nop 0
	global_load_lds_dwordx4 v[236:237], off
	s_cbranch_vccnz .Llw1112pw2
	s_waitcnt vmcnt(8)
.Llw1112pw2:
	s_waitcnt lgkmcnt(0)
	s_barrier
	s_setprio 1
	s_waitcnt lgkmcnt(0)
	v_mfma_f32_16x16x32_bf16 v[124:127], v[144:147], v[186:189], v[124:127]
	v_mfma_f32_16x16x32_bf16 v[120:123], v[160:163], v[186:189], v[120:123]
	v_mfma_f32_16x16x32_bf16 v[108:111], v[144:147], v[194:197], v[108:111]
	v_mfma_f32_16x16x32_bf16 v[104:107], v[160:163], v[194:197], v[104:107]
	v_mfma_f32_16x16x32_bf16 v[92:95], v[144:147], v[202:205], v[92:95]
	v_mfma_f32_16x16x32_bf16 v[88:91], v[160:163], v[202:205], v[88:91]
	v_mfma_f32_16x16x32_bf16 v[76:79], v[144:147], v[210:213], v[76:79]
	v_mfma_f32_16x16x32_bf16 v[72:75], v[160:163], v[210:213], v[72:75]
	v_mfma_f32_16x16x32_bf16 v[124:127], v[156:159], v[190:193], v[124:127]
	v_mfma_f32_16x16x32_bf16 v[120:123], v[164:167], v[190:193], v[120:123]
	v_mfma_f32_16x16x32_bf16 v[108:111], v[156:159], v[198:201], v[108:111]
	v_mfma_f32_16x16x32_bf16 v[104:107], v[164:167], v[198:201], v[104:107]
	v_mfma_f32_16x16x32_bf16 v[92:95], v[156:159], v[206:209], v[92:95]
	v_mfma_f32_16x16x32_bf16 v[88:91], v[164:167], v[206:209], v[88:91]
	v_mfma_f32_16x16x32_bf16 v[76:79], v[156:159], v[214:217], v[76:79]
	v_mfma_f32_16x16x32_bf16 v[72:75], v[164:167], v[214:217], v[72:75]
	s_setprio 0
	s_setprio 1
	v_mfma_f32_16x16x32_bf16 v[116:119], v[168:171], v[186:189], v[116:119]
	v_mfma_f32_16x16x32_bf16 v[112:115], v[176:179], v[186:189], v[112:115]
	v_mfma_f32_16x16x32_bf16 v[100:103], v[168:171], v[194:197], v[100:103]
	v_mfma_f32_16x16x32_bf16 v[96:99], v[176:179], v[194:197], v[96:99]
	v_mfma_f32_16x16x32_bf16 v[84:87], v[168:171], v[202:205], v[84:87]
	v_mfma_f32_16x16x32_bf16 v[80:83], v[176:179], v[202:205], v[80:83]
	v_mfma_f32_16x16x32_bf16 v[68:71], v[168:171], v[210:213], v[68:71]
	v_mfma_f32_16x16x32_bf16 v[64:67], v[176:179], v[210:213], v[64:67]
	v_mfma_f32_16x16x32_bf16 v[116:119], v[172:175], v[190:193], v[116:119]
	v_mfma_f32_16x16x32_bf16 v[112:115], v[180:183], v[190:193], v[112:115]
	v_mfma_f32_16x16x32_bf16 v[100:103], v[172:175], v[198:201], v[100:103]
	v_mfma_f32_16x16x32_bf16 v[96:99], v[180:183], v[198:201], v[96:99]
	v_mfma_f32_16x16x32_bf16 v[84:87], v[172:175], v[206:209], v[84:87]
	v_mfma_f32_16x16x32_bf16 v[80:83], v[180:183], v[206:209], v[80:83]
	v_mfma_f32_16x16x32_bf16 v[68:71], v[172:175], v[214:217], v[68:71]
	v_mfma_f32_16x16x32_bf16 v[64:67], v[180:183], v[214:217], v[64:67]
	s_setprio 0
	s_waitcnt vmcnt(8)
	s_barrier
	s_add_i32 s46, s52, s31
	v_lshl_add_u64 v[224:225], v[224:225], 0, s[36:37]
	s_mov_b32 m0, s46
	ds_read_b128 v[186:189], v153 offset:49152
	ds_read_b128 v[190:193], v153 offset:50176
	ds_read_b128 v[194:197], v153 offset:51200
	ds_read_b128 v[198:201], v153 offset:52224
	ds_read_b128 v[202:205], v153 offset:53248
	ds_read_b128 v[206:209], v153 offset:54272
	ds_read_b128 v[210:213], v153 offset:55296
	ds_read_b128 v[214:217], v153 offset:56320
	global_load_lds_dwordx4 v[224:225], off
	v_lshl_add_u64 v[224:225], v[226:227], 0, s[36:37]
	s_add_i32 m0, s46, 0x2000
	s_add_i32 s46, s53, s31
	global_load_lds_dwordx4 v[224:225], off
	v_lshl_add_u64 v[224:225], v[228:229], 0, s[36:37]
	s_mov_b32 m0, s46
	s_nop 0
	global_load_lds_dwordx4 v[224:225], off
	v_lshl_add_u64 v[224:225], v[230:231], 0, s[36:37]
	s_add_i32 m0, s46, 0x2000
	s_nop 0
	global_load_lds_dwordx4 v[224:225], off
	s_cbranch_vccnz .Llw1112pw3
	s_waitcnt vmcnt(6)
.Llw1112pw3:
	s_waitcnt lgkmcnt(0)
	s_barrier
	s_setprio 1
	s_waitcnt lgkmcnt(0)
	v_mfma_f32_16x16x32_bf16 v[60:63], v[144:147], v[186:189], v[60:63]
	v_mfma_f32_16x16x32_bf16 v[56:59], v[160:163], v[186:189], v[56:59]
	v_mfma_f32_16x16x32_bf16 v[44:47], v[144:147], v[194:197], v[44:47]
	v_mfma_f32_16x16x32_bf16 v[40:43], v[160:163], v[194:197], v[40:43]
	v_mfma_f32_16x16x32_bf16 v[28:31], v[144:147], v[202:205], v[28:31]
	v_mfma_f32_16x16x32_bf16 v[24:27], v[160:163], v[202:205], v[24:27]
	v_mfma_f32_16x16x32_bf16 v[12:15], v[144:147], v[210:213], v[12:15]
	v_mfma_f32_16x16x32_bf16 v[8:11], v[160:163], v[210:213], v[8:11]
	v_mfma_f32_16x16x32_bf16 v[60:63], v[156:159], v[190:193], v[60:63]
	v_mfma_f32_16x16x32_bf16 v[56:59], v[164:167], v[190:193], v[56:59]
	v_mfma_f32_16x16x32_bf16 v[44:47], v[156:159], v[198:201], v[44:47]
	v_mfma_f32_16x16x32_bf16 v[40:43], v[164:167], v[198:201], v[40:43]
	v_mfma_f32_16x16x32_bf16 v[28:31], v[156:159], v[206:209], v[28:31]
	v_mfma_f32_16x16x32_bf16 v[24:27], v[164:167], v[206:209], v[24:27]
	v_mfma_f32_16x16x32_bf16 v[12:15], v[156:159], v[214:217], v[12:15]
	v_mfma_f32_16x16x32_bf16 v[8:11], v[164:167], v[214:217], v[8:11]
	s_setprio 0
	s_setprio 1
	v_mfma_f32_16x16x32_bf16 v[52:55], v[168:171], v[186:189], v[52:55]
	v_mfma_f32_16x16x32_bf16 v[48:51], v[176:179], v[186:189], v[48:51]
	v_mfma_f32_16x16x32_bf16 v[36:39], v[168:171], v[194:197], v[36:39]
	v_mfma_f32_16x16x32_bf16 v[32:35], v[176:179], v[194:197], v[32:35]
	v_mfma_f32_16x16x32_bf16 v[20:23], v[168:171], v[202:205], v[20:23]
	v_mfma_f32_16x16x32_bf16 v[16:19], v[176:179], v[202:205], v[16:19]
	v_mfma_f32_16x16x32_bf16 v[4:7], v[168:171], v[210:213], v[4:7]
	v_mfma_f32_16x16x32_bf16 v[0:3], v[176:179], v[210:213], v[0:3]
	v_mfma_f32_16x16x32_bf16 v[52:55], v[172:175], v[190:193], v[52:55]
	v_mfma_f32_16x16x32_bf16 v[48:51], v[180:183], v[190:193], v[48:51]
	v_mfma_f32_16x16x32_bf16 v[36:39], v[172:175], v[198:201], v[36:39]
	v_mfma_f32_16x16x32_bf16 v[32:35], v[180:183], v[198:201], v[32:35]
	v_mfma_f32_16x16x32_bf16 v[20:23], v[172:175], v[206:209], v[20:23]
	v_mfma_f32_16x16x32_bf16 v[16:19], v[180:183], v[206:209], v[16:19]
	v_mfma_f32_16x16x32_bf16 v[4:7], v[172:175], v[214:217], v[4:7]
	v_mfma_f32_16x16x32_bf16 v[0:3], v[180:183], v[214:217], v[0:3]
	s_setprio 0
	s_waitcnt vmcnt(6)
	s_barrier
	s_add_u32 s4, s4, 0x100
	s_addc_u32 s5, s5, 0
	s_add_u32 s33, s33, 0x100
	s_addc_u32 s48, s48, 0
	s_cmp_ge_i32 s49, s59
	s_mov_b32 s46, s49
	s_cbranch_scc1 .LBB0_1113
.LBB0_1112:
	ds_read_b128 v[144:147], v151
	ds_read_b128 v[156:159], v151 offset:1024
	ds_read_b128 v[160:163], v151 offset:2048
	ds_read_b128 v[164:167], v151 offset:3072
	ds_read_b128 v[168:171], v152
	ds_read_b128 v[172:175], v152 offset:1024
	ds_read_b128 v[176:179], v152 offset:2048
	ds_read_b128 v[180:183], v152 offset:3072
	s_add_i32 s49, s46, 2
	s_add_u32 s52, s4, 0x80
	s_addc_u32 s47, s5, 0
	s_cmp_eq_u32 s60, s46
	s_cselect_b32 s46, s42, s52
	s_cselect_b32 s47, s43, s47
	s_cselect_b32 s53, s45, s48
	s_cselect_b32 s52, s44, s33
	v_lshl_add_u64 v[224:225], v[232:233], 0, s[36:37]
	s_mov_b32 m0, s57
	s_nop 0
	global_load_lds_dwordx4 v[224:225], off
	v_lshl_add_u64 v[224:225], v[234:235], 0, s[36:37]
	s_mov_b32 m0, s58
	s_nop 0
	global_load_lds_dwordx4 v[224:225], off
	v_lshl_add_u64 v[224:225], s[4:5], 0, v[136:137]
	s_add_i32 m0, s50, 0xc000
	ds_read_b128 v[186:189], v153
	ds_read_b128 v[190:193], v153 offset:1024
	ds_read_b128 v[194:197], v153 offset:2048
	ds_read_b128 v[198:201], v153 offset:3072
	ds_read_b128 v[202:205], v153 offset:4096
	ds_read_b128 v[206:209], v153 offset:5120
	ds_read_b128 v[210:213], v153 offset:6144
	ds_read_b128 v[214:217], v153 offset:7168
	global_load_lds_dwordx4 v[224:225], off
	v_lshl_add_u64 v[224:225], s[4:5], 0, v[138:139]
	s_add_i32 m0, s50, 0xe000
	s_nop 0
	global_load_lds_dwordx4 v[224:225], off
	s_cbranch_vccnz .Llw1112bw0
	s_waitcnt vmcnt(8)
.Llw1112bw0:
	s_waitcnt lgkmcnt(0)
	s_barrier
	s_setprio 1
	s_waitcnt lgkmcnt(0)
	v_mfma_f32_16x16x32_bf16 v[124:127], v[144:147], v[186:189], v[124:127]
	v_mfma_f32_16x16x32_bf16 v[120:123], v[160:163], v[186:189], v[120:123]
	v_mfma_f32_16x16x32_bf16 v[108:111], v[144:147], v[194:197], v[108:111]
	v_mfma_f32_16x16x32_bf16 v[104:107], v[160:163], v[194:197], v[104:107]
	v_mfma_f32_16x16x32_bf16 v[92:95], v[144:147], v[202:205], v[92:95]
	v_mfma_f32_16x16x32_bf16 v[88:91], v[160:163], v[202:205], v[88:91]
	v_mfma_f32_16x16x32_bf16 v[76:79], v[144:147], v[210:213], v[76:79]
	v_mfma_f32_16x16x32_bf16 v[72:75], v[160:163], v[210:213], v[72:75]
	v_mfma_f32_16x16x32_bf16 v[124:127], v[156:159], v[190:193], v[124:127]
	v_mfma_f32_16x16x32_bf16 v[120:123], v[164:167], v[190:193], v[120:123]
	v_mfma_f32_16x16x32_bf16 v[108:111], v[156:159], v[198:201], v[108:111]
	v_mfma_f32_16x16x32_bf16 v[104:107], v[164:167], v[198:201], v[104:107]
	v_mfma_f32_16x16x32_bf16 v[92:95], v[156:159], v[206:209], v[92:95]
	v_mfma_f32_16x16x32_bf16 v[88:91], v[164:167], v[206:209], v[88:91]
	v_mfma_f32_16x16x32_bf16 v[76:79], v[156:159], v[214:217], v[76:79]
	v_mfma_f32_16x16x32_bf16 v[72:75], v[164:167], v[214:217], v[72:75]
	s_setprio 0
	s_setprio 1
	v_mfma_f32_16x16x32_bf16 v[116:119], v[168:171], v[186:189], v[116:119]
	v_mfma_f32_16x16x32_bf16 v[112:115], v[176:179], v[186:189], v[112:115]
	v_mfma_f32_16x16x32_bf16 v[100:103], v[168:171], v[194:197], v[100:103]
	v_mfma_f32_16x16x32_bf16 v[96:99], v[176:179], v[194:197], v[96:99]
	v_mfma_f32_16x16x32_bf16 v[84:87], v[168:171], v[202:205], v[84:87]
	v_mfma_f32_16x16x32_bf16 v[80:83], v[176:179], v[202:205], v[80:83]
	v_mfma_f32_16x16x32_bf16 v[68:71], v[168:171], v[210:213], v[68:71]
	v_mfma_f32_16x16x32_bf16 v[64:67], v[176:179], v[210:213], v[64:67]
	v_mfma_f32_16x16x32_bf16 v[116:119], v[172:175], v[190:193], v[116:119]
	v_mfma_f32_16x16x32_bf16 v[112:115], v[180:183], v[190:193], v[112:115]
	v_mfma_f32_16x16x32_bf16 v[100:103], v[172:175], v[198:201], v[100:103]
	v_mfma_f32_16x16x32_bf16 v[96:99], v[180:183], v[198:201], v[96:99]
	v_mfma_f32_16x16x32_bf16 v[84:87], v[172:175], v[206:209], v[84:87]
	v_mfma_f32_16x16x32_bf16 v[80:83], v[180:183], v[206:209], v[80:83]
	v_mfma_f32_16x16x32_bf16 v[68:71], v[172:175], v[214:217], v[68:71]
	v_mfma_f32_16x16x32_bf16 v[64:67], v[180:183], v[214:217], v[64:67]
	s_setprio 0
	s_waitcnt vmcnt(8)
	s_barrier
	s_add_i32 s65, s61, s31
	v_lshl_add_u64 v[224:225], s[52:53], 0, v[130:131]
	s_mov_b32 m0, s65
	ds_read_b128 v[186:189], v153 offset:16384
	ds_read_b128 v[190:193], v153 offset:17408
	ds_read_b128 v[194:197], v153 offset:18432
	ds_read_b128 v[198:201], v153 offset:19456
	ds_read_b128 v[202:205], v153 offset:20480
	ds_read_b128 v[206:209], v153 offset:21504
	ds_read_b128 v[210:213], v153 offset:22528
	ds_read_b128 v[214:217], v153 offset:23552
	global_load_lds_dwordx4 v[224:225], off
	s_add_i32 m0, s65, 0x2000
	v_lshl_add_u64 v[226:227], s[52:53], 0, v[134:135]
	s_add_u32 s52, s52, s14
	s_addc_u32 s53, s53, s15
	s_add_i32 s65, s62, s31
	global_load_lds_dwordx4 v[226:227], off
	v_lshl_add_u64 v[228:229], s[52:53], 0, v[130:131]
	s_mov_b32 m0, s65
	v_lshl_add_u64 v[230:231], s[52:53], 0, v[134:135]
	global_load_lds_dwordx4 v[228:229], off
	s_add_i32 m0, s65, 0x2000
	v_lshl_add_u64 v[232:233], s[46:47], 0, v[128:129]
	global_load_lds_dwordx4 v[230:231], off
	v_lshl_add_u64 v[234:235], s[46:47], 0, v[132:133]
	s_cbranch_vccnz .Llw1112bw1
	s_waitcnt vmcnt(6)
.Llw1112bw1:
	s_waitcnt lgkmcnt(0)
	s_barrier
	s_setprio 1
	s_waitcnt lgkmcnt(0)
	v_mfma_f32_16x16x32_bf16 v[60:63], v[144:147], v[186:189], v[60:63]
	v_mfma_f32_16x16x32_bf16 v[56:59], v[160:163], v[186:189], v[56:59]
	v_mfma_f32_16x16x32_bf16 v[44:47], v[144:147], v[194:197], v[44:47]
	v_mfma_f32_16x16x32_bf16 v[40:43], v[160:163], v[194:197], v[40:43]
	v_mfma_f32_16x16x32_bf16 v[28:31], v[144:147], v[202:205], v[28:31]
	v_mfma_f32_16x16x32_bf16 v[24:27], v[160:163], v[202:205], v[24:27]
	v_mfma_f32_16x16x32_bf16 v[12:15], v[144:147], v[210:213], v[12:15]
	v_mfma_f32_16x16x32_bf16 v[8:11], v[160:163], v[210:213], v[8:11]
	v_mfma_f32_16x16x32_bf16 v[60:63], v[156:159], v[190:193], v[60:63]
	v_mfma_f32_16x16x32_bf16 v[56:59], v[164:167], v[190:193], v[56:59]
	v_mfma_f32_16x16x32_bf16 v[44:47], v[156:159], v[198:201], v[44:47]
	v_mfma_f32_16x16x32_bf16 v[40:43], v[164:167], v[198:201], v[40:43]
	v_mfma_f32_16x16x32_bf16 v[28:31], v[156:159], v[206:209], v[28:31]
	v_mfma_f32_16x16x32_bf16 v[24:27], v[164:167], v[206:209], v[24:27]
	v_mfma_f32_16x16x32_bf16 v[12:15], v[156:159], v[214:217], v[12:15]
	v_mfma_f32_16x16x32_bf16 v[8:11], v[164:167], v[214:217], v[8:11]
	s_setprio 0
	s_setprio 1
	v_mfma_f32_16x16x32_bf16 v[52:55], v[168:171], v[186:189], v[52:55]
	v_mfma_f32_16x16x32_bf16 v[48:51], v[176:179], v[186:189], v[48:51]
	v_mfma_f32_16x16x32_bf16 v[36:39], v[168:171], v[194:197], v[36:39]
	v_mfma_f32_16x16x32_bf16 v[32:35], v[176:179], v[194:197], v[32:35]
	v_mfma_f32_16x16x32_bf16 v[20:23], v[168:171], v[202:205], v[20:23]
	v_mfma_f32_16x16x32_bf16 v[16:19], v[176:179], v[202:205], v[16:19]
	v_mfma_f32_16x16x32_bf16 v[4:7], v[168:171], v[210:213], v[4:7]
	v_mfma_f32_16x16x32_bf16 v[0:3], v[176:179], v[210:213], v[0:3]
	v_mfma_f32_16x16x32_bf16 v[52:55], v[172:175], v[190:193], v[52:55]
	v_mfma_f32_16x16x32_bf16 v[48:51], v[180:183], v[190:193], v[48:51]
	v_mfma_f32_16x16x32_bf16 v[36:39], v[172:175], v[198:201], v[36:39]
	v_mfma_f32_16x16x32_bf16 v[32:35], v[180:183], v[198:201], v[32:35]
	v_mfma_f32_16x16x32_bf16 v[20:23], v[172:175], v[206:209], v[20:23]
	v_mfma_f32_16x16x32_bf16 v[16:19], v[180:183], v[206:209], v[16:19]
	v_mfma_f32_16x16x32_bf16 v[4:7], v[172:175], v[214:217], v[4:7]
	v_mfma_f32_16x16x32_bf16 v[0:3], v[180:183], v[214:217], v[0:3]
	s_setprio 0
	s_waitcnt vmcnt(6)
	s_barrier
	s_add_i32 s52, 0, 0x18000
	v_add_u32_e32 v155, s52, v149
	s_add_i32 s53, 0, 0x1c000
	ds_read_b128 v[144:147], v155
	ds_read_b128 v[156:159], v155 offset:1024
	ds_read_b128 v[160:163], v155 offset:2048
	ds_read_b128 v[164:167], v155 offset:3072
	v_add_u32_e32 v155, s53, v149
	ds_read_b128 v[168:171], v155
	ds_read_b128 v[172:175], v155 offset:1024
	ds_read_b128 v[176:179], v155 offset:2048
	ds_read_b128 v[180:183], v155 offset:3072
	s_add_u32 s46, s46, s14
	s_addc_u32 s47, s47, s15
	s_mov_b32 m0, s50
	s_nop 0
	global_load_lds_dwordx4 v[232:233], off
	s_mov_b32 m0, s51
	s_nop 0
	global_load_lds_dwordx4 v[234:235], off
	s_mov_b32 m0, s54
	v_lshl_add_u64 v[236:237], s[46:47], 0, v[128:129]
	ds_read_b128 v[186:189], v153 offset:32768
	ds_read_b128 v[190:193], v153 offset:33792
	ds_read_b128 v[194:197], v153 offset:34816
	ds_read_b128 v[198:201], v153 offset:35840
	ds_read_b128 v[202:205], v153 offset:36864
	ds_read_b128 v[206:209], v153 offset:37888
	ds_read_b128 v[210:213], v153 offset:38912
	ds_read_b128 v[214:217], v153 offset:39936
	global_load_lds_dwordx4 v[236:237], off
	v_lshl_add_u64 v[236:237], s[46:47], 0, v[132:133]
	s_mov_b32 m0, s55
	s_nop 0
	global_load_lds_dwordx4 v[236:237], off
	s_cbranch_vccnz .Llw1112bw2
	s_waitcnt vmcnt(8)

.Llw1112bw3:
	s_waitcnt lgkmcnt(0)
	s_barrier
	s_setprio 1
	s_waitcnt lgkmcnt(0)
	v_mfma_f32_16x16x32_bf16 v[60:63], v[144:147], v[186:189], v[60:63]
	v_mfma_f32_16x16x32_bf16 v[56:59], v[160:163], v[186:189], v[56:59]
	v_mfma_f32_16x16x32_bf16 v[44:47], v[144:147], v[194:197], v[44:47]
	v_mfma_f32_16x16x32_bf16 v[40:43], v[160:163], v[194:197], v[40:43]
	v_mfma_f32_16x16x32_bf16 v[28:31], v[144:147], v[202:205], v[28:31]
	v_mfma_f32_16x16x32_bf16 v[24:27], v[160:163], v[202:205], v[24:27]
	v_mfma_f32_16x16x32_bf16 v[12:15], v[144:147], v[210:213], v[12:15]
	v_mfma_f32_16x16x32_bf16 v[8:11], v[160:163], v[210:213], v[8:11]
	v_mfma_f32_16x16x32_bf16 v[60:63], v[156:159], v[190:193], v[60:63]
	v_mfma_f32_16x16x32_bf16 v[56:59], v[164:167], v[190:193], v[56:59]
	v_mfma_f32_16x16x32_bf16 v[44:47], v[156:159], v[198:201], v[44:47]
	v_mfma_f32_16x16x32_bf16 v[40:43], v[164:167], v[198:201], v[40:43]
	v_mfma_f32_16x16x32_bf16 v[28:31], v[156:159], v[206:209], v[28:31]
	v_mfma_f32_16x16x32_bf16 v[24:27], v[164:167], v[206:209], v[24:27]
	v_mfma_f32_16x16x32_bf16 v[12:15], v[156:159], v[214:217], v[12:15]
	v_mfma_f32_16x16x32_bf16 v[8:11], v[164:167], v[214:217], v[8:11]
	s_setprio 0
	s_setprio 1
	v_mfma_f32_16x16x32_bf16 v[52:55], v[168:171], v[186:189], v[52:55]
	v_mfma_f32_16x16x32_bf16 v[48:51], v[176:179], v[186:189], v[48:51]
	v_mfma_f32_16x16x32_bf16 v[36:39], v[168:171], v[194:197], v[36:39]
	v_mfma_f32_16x16x32_bf16 v[32:35], v[176:179], v[194:197], v[32:35]
	v_mfma_f32_16x16x32_bf16 v[20:23], v[168:171], v[202:205], v[20:23]
	v_mfma_f32_16x16x32_bf16 v[16:19], v[176:179], v[202:205], v[16:19]
	v_mfma_f32_16x16x32_bf16 v[4:7], v[168:171], v[210:213], v[4:7]
	v_mfma_f32_16x16x32_bf16 v[0:3], v[176:179], v[210:213], v[0:3]
	v_mfma_f32_16x16x32_bf16 v[52:55], v[172:175], v[190:193], v[52:55]
	v_mfma_f32_16x16x32_bf16 v[48:51], v[180:183], v[190:193], v[48:51]
	v_mfma_f32_16x16x32_bf16 v[36:39], v[172:175], v[198:201], v[36:39]
	v_mfma_f32_16x16x32_bf16 v[32:35], v[180:183], v[198:201], v[32:35]
	v_mfma_f32_16x16x32_bf16 v[20:23], v[172:175], v[206:209], v[20:23]
	v_mfma_f32_16x16x32_bf16 v[16:19], v[180:183], v[206:209], v[16:19]
	v_mfma_f32_16x16x32_bf16 v[4:7], v[172:175], v[214:217], v[4:7]
	v_mfma_f32_16x16x32_bf16 v[0:3], v[180:183], v[214:217], v[0:3]
	s_setprio 0
	s_waitcnt vmcnt(6)
	s_barrier
	s_add_u32 s4, s4, 0x100
	s_addc_u32 s5, s5, 0
	s_add_u32 s33, s33, 0x100
	s_addc_u32 s48, s48, 0
	s_cmp_ge_i32 s49, s59
	s_mov_b32 s46, s49
	s_cbranch_scc0 .LBB0_1112
	s_branch .LBB0_1113
